# s_setprio flips removed from the K loops of all four GEMM phases (in-proj, out-proj, up-proj, down-proj)
# speedup vs baseline: 1.0062x; 1.0016x over previous
.LBB0_171:
	ds_read_b128 v[176:179], v167
	ds_read_b128 v[180:183], v167 offset:1024
	ds_read_b128 v[184:187], v167 offset:2048
	ds_read_b128 v[188:191], v167 offset:3072
	v_add_u32_e32 v157, 0xc000, v161
	v_lshl_add_u64 v[196:197], s[10:11], 0, v[148:149]
	v_readfirstlane_b32 s4, v157
	v_add_u32_e32 v175, 0xe000, v161
	v_lshl_add_u64 v[228:229], v[196:197], 0, s[36:37]
	s_mov_b32 m0, s4
	v_lshl_add_u64 v[244:245], s[10:11], 0, v[150:151]
	v_readfirstlane_b32 s4, v175
	ds_read_b128 v[192:195], v168
	ds_read_b128 v[200:203], v168 offset:1024
	ds_read_b128 v[204:207], v169
	ds_read_b128 v[208:211], v169 offset:1024
	ds_read_b128 v[212:215], v170
	ds_read_b128 v[216:219], v170 offset:1024
	ds_read_b128 v[220:223], v171
	ds_read_b128 v[224:227], v171 offset:1024
	global_load_lds_dwordx4 v[228:229], off
	v_lshl_add_u64 v[228:229], v[244:245], 0, s[36:37]
	s_mov_b32 m0, s4
	s_nop 0
	global_load_lds_dwordx4 v[228:229], off
	s_waitcnt lgkmcnt(8)
	s_barrier
	s_waitcnt lgkmcnt(0)
	s_waitcnt lgkmcnt(0)
	v_mfma_f32_16x16x32_bf16 v[126:129], v[176:179], v[192:195], v[126:129]
	v_mfma_f32_16x16x32_bf16 v[122:125], v[184:187], v[192:195], v[122:125]
	v_mfma_f32_16x16x32_bf16 v[118:121], v[176:179], v[204:207], v[118:121]
	v_mfma_f32_16x16x32_bf16 v[114:117], v[184:187], v[204:207], v[114:117]
	v_mfma_f32_16x16x32_bf16 v[110:113], v[176:179], v[212:215], v[110:113]
	v_mfma_f32_16x16x32_bf16 v[106:109], v[184:187], v[212:215], v[106:109]
	v_mfma_f32_16x16x32_bf16 v[102:105], v[176:179], v[220:223], v[102:105]
	v_mfma_f32_16x16x32_bf16 v[98:101], v[184:187], v[220:223], v[98:101]
	v_mfma_f32_16x16x32_bf16 v[126:129], v[180:183], v[200:203], v[126:129]
	v_mfma_f32_16x16x32_bf16 v[122:125], v[188:191], v[200:203], v[122:125]
	v_mfma_f32_16x16x32_bf16 v[118:121], v[180:183], v[208:211], v[118:121]
	v_mfma_f32_16x16x32_bf16 v[114:117], v[188:191], v[208:211], v[114:117]
	v_mfma_f32_16x16x32_bf16 v[110:113], v[180:183], v[216:219], v[110:113]
	v_mfma_f32_16x16x32_bf16 v[106:109], v[188:191], v[216:219], v[106:109]
	v_mfma_f32_16x16x32_bf16 v[102:105], v[180:183], v[224:227], v[102:105]
	v_mfma_f32_16x16x32_bf16 v[98:101], v[188:191], v[224:227], v[98:101]
	s_barrier
	v_lshl_add_u64 v[246:247], s[10:11], 0, v[144:145]
	v_readfirstlane_b32 s4, v159
	v_lshl_add_u64 v[248:249], v[246:247], 0, s[38:39]
	s_mov_b32 m0, s4
	ds_read_b128 v[228:231], v172
	ds_read_b128 v[232:235], v172 offset:1024
	ds_read_b128 v[236:239], v172 offset:2048
	ds_read_b128 v[240:243], v172 offset:3072
	global_load_lds_dwordx4 v[248:249], off
	v_lshl_add_u64 v[248:249], s[10:11], 0, v[146:147]
	v_readfirstlane_b32 s4, v160
	v_lshl_add_u64 v[250:251], v[248:249], 0, s[38:39]
	s_mov_b32 m0, s4
	s_nop 0
	global_load_lds_dwordx4 v[250:251], off
	s_barrier
	s_waitcnt lgkmcnt(0)
	s_waitcnt lgkmcnt(0)
	v_mfma_f32_16x16x32_bf16 v[94:97], v[228:231], v[192:195], v[94:97]
	v_mfma_f32_16x16x32_bf16 v[90:93], v[236:239], v[192:195], v[90:93]
	v_mfma_f32_16x16x32_bf16 v[86:89], v[228:231], v[204:207], v[86:89]
	v_mfma_f32_16x16x32_bf16 v[82:85], v[236:239], v[204:207], v[82:85]
	v_mfma_f32_16x16x32_bf16 v[78:81], v[228:231], v[212:215], v[78:81]
	v_mfma_f32_16x16x32_bf16 v[74:77], v[236:239], v[212:215], v[74:77]
	v_mfma_f32_16x16x32_bf16 v[70:73], v[228:231], v[220:223], v[70:73]
	v_mfma_f32_16x16x32_bf16 v[66:69], v[236:239], v[220:223], v[66:69]
	v_mfma_f32_16x16x32_bf16 v[94:97], v[232:235], v[200:203], v[94:97]
	v_mfma_f32_16x16x32_bf16 v[90:93], v[240:243], v[200:203], v[90:93]
	v_mfma_f32_16x16x32_bf16 v[86:89], v[232:235], v[208:211], v[86:89]
	v_mfma_f32_16x16x32_bf16 v[82:85], v[240:243], v[208:211], v[82:85]
	v_mfma_f32_16x16x32_bf16 v[78:81], v[232:235], v[216:219], v[78:81]
	v_mfma_f32_16x16x32_bf16 v[74:77], v[240:243], v[216:219], v[74:77]
	v_mfma_f32_16x16x32_bf16 v[70:73], v[232:235], v[224:227], v[70:73]
	v_mfma_f32_16x16x32_bf16 v[66:69], v[240:243], v[224:227], v[66:69]
	v_readfirstlane_b32 s4, v161
	v_lshl_add_u64 v[250:251], v[196:197], 0, s[58:59]
	s_mov_b32 m0, s4
	v_readfirstlane_b32 s4, v162
	s_barrier
	ds_read_b128 v[192:195], v168 offset:16384
	ds_read_b128 v[200:203], v168 offset:17408
	ds_read_b128 v[204:207], v169 offset:16384
	ds_read_b128 v[208:211], v169 offset:17408
	ds_read_b128 v[212:215], v170 offset:16384
	ds_read_b128 v[216:219], v170 offset:17408
	ds_read_b128 v[220:223], v171 offset:16384
	ds_read_b128 v[224:227], v171 offset:17408
	global_load_lds_dwordx4 v[250:251], off
	v_lshl_add_u64 v[250:251], v[244:245], 0, s[58:59]
	s_mov_b32 m0, s4
	s_nop 0
	global_load_lds_dwordx4 v[250:251], off
	s_barrier
	s_waitcnt lgkmcnt(0)
	s_waitcnt lgkmcnt(0)
	v_mfma_f32_16x16x32_bf16 v[62:65], v[176:179], v[192:195], v[62:65]
	v_mfma_f32_16x16x32_bf16 v[58:61], v[184:187], v[192:195], v[58:61]
	v_mfma_f32_16x16x32_bf16 v[54:57], v[176:179], v[204:207], v[54:57]
	v_mfma_f32_16x16x32_bf16 v[50:53], v[184:187], v[204:207], v[50:53]
	v_mfma_f32_16x16x32_bf16 v[46:49], v[176:179], v[212:215], v[46:49]
	v_mfma_f32_16x16x32_bf16 v[42:45], v[184:187], v[212:215], v[42:45]
	v_mfma_f32_16x16x32_bf16 v[38:41], v[176:179], v[220:223], v[38:41]
	v_mfma_f32_16x16x32_bf16 v[34:37], v[184:187], v[220:223], v[34:37]
	v_mfma_f32_16x16x32_bf16 v[62:65], v[180:183], v[200:203], v[62:65]
	v_mfma_f32_16x16x32_bf16 v[58:61], v[188:191], v[200:203], v[58:61]
	v_mfma_f32_16x16x32_bf16 v[54:57], v[180:183], v[208:211], v[54:57]
	v_mfma_f32_16x16x32_bf16 v[50:53], v[188:191], v[208:211], v[50:53]
	v_mfma_f32_16x16x32_bf16 v[46:49], v[180:183], v[216:219], v[46:49]
	v_mfma_f32_16x16x32_bf16 v[42:45], v[188:191], v[216:219], v[42:45]
	v_mfma_f32_16x16x32_bf16 v[38:41], v[180:183], v[224:227], v[38:41]
	v_mfma_f32_16x16x32_bf16 v[34:37], v[188:191], v[224:227], v[34:37]
	s_barrier
	v_readfirstlane_b32 s4, v163
	v_lshl_add_u64 v[176:177], v[246:247], 0, s[60:61]
	s_mov_b32 m0, s4
	v_readfirstlane_b32 s4, v164
	global_load_lds_dwordx4 v[176:177], off
	v_lshl_add_u64 v[176:177], v[248:249], 0, s[60:61]
	s_mov_b32 m0, s4
	s_nop 0
	global_load_lds_dwordx4 v[176:177], off
	s_waitcnt vmcnt(6)
	s_barrier
	v_mfma_f32_16x16x32_bf16 v[30:33], v[228:231], v[192:195], v[30:33]
	v_mfma_f32_16x16x32_bf16 v[26:29], v[236:239], v[192:195], v[26:29]
	v_mfma_f32_16x16x32_bf16 v[22:25], v[228:231], v[204:207], v[22:25]
	v_mfma_f32_16x16x32_bf16 v[18:21], v[236:239], v[204:207], v[18:21]
	v_mfma_f32_16x16x32_bf16 v[14:17], v[228:231], v[212:215], v[14:17]
	v_mfma_f32_16x16x32_bf16 v[10:13], v[236:239], v[212:215], v[10:13]
	v_mfma_f32_16x16x32_bf16 v[6:9], v[228:231], v[220:223], v[6:9]
	v_mfma_f32_16x16x32_bf16 v[2:5], v[236:239], v[220:223], v[2:5]
	v_mfma_f32_16x16x32_bf16 v[30:33], v[232:235], v[200:203], v[30:33]
	v_mfma_f32_16x16x32_bf16 v[26:29], v[240:243], v[200:203], v[26:29]
	v_mfma_f32_16x16x32_bf16 v[22:25], v[232:235], v[208:211], v[22:25]
	v_mfma_f32_16x16x32_bf16 v[18:21], v[240:243], v[208:211], v[18:21]
	v_mfma_f32_16x16x32_bf16 v[14:17], v[232:235], v[216:219], v[14:17]
	v_mfma_f32_16x16x32_bf16 v[10:13], v[240:243], v[216:219], v[10:13]
	v_mfma_f32_16x16x32_bf16 v[6:9], v[232:235], v[224:227], v[6:9]
	v_mfma_f32_16x16x32_bf16 v[2:5], v[240:243], v[224:227], v[2:5]
	s_barrier
	ds_read_b128 v[176:179], v173
	ds_read_b128 v[180:183], v173 offset:1024
	ds_read_b128 v[184:187], v173 offset:2048
	ds_read_b128 v[188:191], v173 offset:3072
	v_readfirstlane_b32 s4, v165
	v_lshl_add_u64 v[228:229], v[196:197], 0, s[62:63]
	s_mov_b32 m0, s4
	v_readfirstlane_b32 s4, v166
	ds_read_b128 v[192:195], v168 offset:32768
	ds_read_b128 v[200:203], v168 offset:33792
	ds_read_b128 v[204:207], v169 offset:32768
	ds_read_b128 v[208:211], v169 offset:33792
	ds_read_b128 v[212:215], v170 offset:32768
	ds_read_b128 v[216:219], v170 offset:33792
	ds_read_b128 v[220:223], v171 offset:32768
	ds_read_b128 v[224:227], v171 offset:33792
	global_load_lds_dwordx4 v[228:229], off
	v_lshl_add_u64 v[228:229], v[244:245], 0, s[62:63]
	s_mov_b32 m0, s4
	s_nop 0
	global_load_lds_dwordx4 v[228:229], off
	s_waitcnt lgkmcnt(8)
	s_barrier
	s_waitcnt lgkmcnt(0)
	s_waitcnt lgkmcnt(0)
	v_mfma_f32_16x16x32_bf16 v[126:129], v[176:179], v[192:195], v[126:129]
	v_mfma_f32_16x16x32_bf16 v[122:125], v[184:187], v[192:195], v[122:125]
	v_mfma_f32_16x16x32_bf16 v[118:121], v[176:179], v[204:207], v[118:121]
	v_mfma_f32_16x16x32_bf16 v[114:117], v[184:187], v[204:207], v[114:117]
	v_mfma_f32_16x16x32_bf16 v[110:113], v[176:179], v[212:215], v[110:113]
	v_mfma_f32_16x16x32_bf16 v[106:109], v[184:187], v[212:215], v[106:109]
	v_mfma_f32_16x16x32_bf16 v[102:105], v[176:179], v[220:223], v[102:105]
	v_mfma_f32_16x16x32_bf16 v[98:101], v[184:187], v[220:223], v[98:101]
	v_mfma_f32_16x16x32_bf16 v[126:129], v[180:183], v[200:203], v[126:129]
	v_mfma_f32_16x16x32_bf16 v[122:125], v[188:191], v[200:203], v[122:125]
	v_mfma_f32_16x16x32_bf16 v[118:121], v[180:183], v[208:211], v[118:121]
	v_mfma_f32_16x16x32_bf16 v[114:117], v[188:191], v[208:211], v[114:117]
	v_mfma_f32_16x16x32_bf16 v[110:113], v[180:183], v[216:219], v[110:113]
	v_mfma_f32_16x16x32_bf16 v[106:109], v[188:191], v[216:219], v[106:109]
	v_mfma_f32_16x16x32_bf16 v[102:105], v[180:183], v[224:227], v[102:105]
	v_mfma_f32_16x16x32_bf16 v[98:101], v[188:191], v[224:227], v[98:101]
	s_barrier
	v_readfirstlane_b32 s4, v134
	v_lshl_add_u64 v[250:251], v[246:247], 0, s[66:67]
	s_mov_b32 m0, s4
	v_readfirstlane_b32 s4, v152
	ds_read_b128 v[228:231], v174
	ds_read_b128 v[232:235], v174 offset:1024
	ds_read_b128 v[236:239], v174 offset:2048
	ds_read_b128 v[240:243], v174 offset:3072
	global_load_lds_dwordx4 v[250:251], off
	v_lshl_add_u64 v[250:251], v[248:249], 0, s[66:67]
	s_mov_b32 m0, s4
	s_nop 0
	global_load_lds_dwordx4 v[250:251], off
	s_barrier
	s_waitcnt lgkmcnt(0)
	s_waitcnt lgkmcnt(0)
	v_mfma_f32_16x16x32_bf16 v[94:97], v[228:231], v[192:195], v[94:97]
	v_mfma_f32_16x16x32_bf16 v[90:93], v[236:239], v[192:195], v[90:93]
	v_mfma_f32_16x16x32_bf16 v[86:89], v[228:231], v[204:207], v[86:89]
	v_mfma_f32_16x16x32_bf16 v[82:85], v[236:239], v[204:207], v[82:85]
	v_mfma_f32_16x16x32_bf16 v[78:81], v[228:231], v[212:215], v[78:81]
	v_mfma_f32_16x16x32_bf16 v[74:77], v[236:239], v[212:215], v[74:77]
	v_mfma_f32_16x16x32_bf16 v[70:73], v[228:231], v[220:223], v[70:73]
	v_mfma_f32_16x16x32_bf16 v[66:69], v[236:239], v[220:223], v[66:69]
	v_mfma_f32_16x16x32_bf16 v[94:97], v[232:235], v[200:203], v[94:97]
	v_mfma_f32_16x16x32_bf16 v[90:93], v[240:243], v[200:203], v[90:93]
	v_mfma_f32_16x16x32_bf16 v[86:89], v[232:235], v[208:211], v[86:89]
	v_mfma_f32_16x16x32_bf16 v[82:85], v[240:243], v[208:211], v[82:85]
	v_mfma_f32_16x16x32_bf16 v[78:81], v[232:235], v[216:219], v[78:81]
	v_mfma_f32_16x16x32_bf16 v[74:77], v[240:243], v[216:219], v[74:77]
	v_mfma_f32_16x16x32_bf16 v[70:73], v[232:235], v[224:227], v[70:73]
	v_mfma_f32_16x16x32_bf16 v[66:69], v[240:243], v[224:227], v[66:69]
	v_readfirstlane_b32 s4, v153
	v_lshl_add_u64 v[196:197], v[196:197], 0, s[68:69]
	s_mov_b32 m0, s4
	v_readfirstlane_b32 s4, v154
	s_barrier
	ds_read_b128 v[192:195], v168 offset:49152
	ds_read_b128 v[200:203], v168 offset:50176
	ds_read_b128 v[204:207], v169 offset:49152
	ds_read_b128 v[208:211], v169 offset:50176
	ds_read_b128 v[212:215], v170 offset:49152
	ds_read_b128 v[216:219], v170 offset:50176
	ds_read_b128 v[220:223], v171 offset:49152
	ds_read_b128 v[224:227], v171 offset:50176
	global_load_lds_dwordx4 v[196:197], off
	v_lshl_add_u64 v[196:197], v[244:245], 0, s[68:69]
	s_mov_b32 m0, s4
	s_nop 0
	global_load_lds_dwordx4 v[196:197], off
	s_barrier
	s_waitcnt lgkmcnt(0)
	s_waitcnt lgkmcnt(0)
	v_mfma_f32_16x16x32_bf16 v[62:65], v[176:179], v[192:195], v[62:65]
	v_mfma_f32_16x16x32_bf16 v[58:61], v[184:187], v[192:195], v[58:61]
	v_mfma_f32_16x16x32_bf16 v[54:57], v[176:179], v[204:207], v[54:57]
	v_mfma_f32_16x16x32_bf16 v[50:53], v[184:187], v[204:207], v[50:53]
	v_mfma_f32_16x16x32_bf16 v[46:49], v[176:179], v[212:215], v[46:49]
	v_mfma_f32_16x16x32_bf16 v[42:45], v[184:187], v[212:215], v[42:45]
	v_mfma_f32_16x16x32_bf16 v[38:41], v[176:179], v[220:223], v[38:41]
	v_mfma_f32_16x16x32_bf16 v[34:37], v[184:187], v[220:223], v[34:37]
	v_mfma_f32_16x16x32_bf16 v[62:65], v[180:183], v[200:203], v[62:65]
	v_mfma_f32_16x16x32_bf16 v[58:61], v[188:191], v[200:203], v[58:61]
	v_mfma_f32_16x16x32_bf16 v[54:57], v[180:183], v[208:211], v[54:57]
	v_mfma_f32_16x16x32_bf16 v[50:53], v[188:191], v[208:211], v[50:53]
	v_mfma_f32_16x16x32_bf16 v[46:49], v[180:183], v[216:219], v[46:49]
	v_mfma_f32_16x16x32_bf16 v[42:45], v[188:191], v[216:219], v[42:45]
	v_mfma_f32_16x16x32_bf16 v[38:41], v[180:183], v[224:227], v[38:41]
	v_mfma_f32_16x16x32_bf16 v[34:37], v[188:191], v[224:227], v[34:37]
	s_barrier
	v_readfirstlane_b32 s4, v155
	v_lshl_add_u64 v[176:177], v[246:247], 0, s[70:71]
	s_mov_b32 m0, s4
	v_readfirstlane_b32 s4, v156
	global_load_lds_dwordx4 v[176:177], off
	v_lshl_add_u64 v[176:177], v[248:249], 0, s[70:71]
	s_mov_b32 m0, s4
	s_nop 0
	global_load_lds_dwordx4 v[176:177], off
	s_waitcnt vmcnt(6)
	s_barrier
	v_mfma_f32_16x16x32_bf16 v[30:33], v[228:231], v[192:195], v[30:33]
	v_mfma_f32_16x16x32_bf16 v[26:29], v[236:239], v[192:195], v[26:29]
	v_mfma_f32_16x16x32_bf16 v[22:25], v[228:231], v[204:207], v[22:25]
	v_mfma_f32_16x16x32_bf16 v[18:21], v[236:239], v[204:207], v[18:21]
	v_mfma_f32_16x16x32_bf16 v[14:17], v[228:231], v[212:215], v[14:17]
	v_mfma_f32_16x16x32_bf16 v[10:13], v[236:239], v[212:215], v[10:13]
	v_mfma_f32_16x16x32_bf16 v[6:9], v[228:231], v[220:223], v[6:9]
	v_mfma_f32_16x16x32_bf16 v[2:5], v[236:239], v[220:223], v[2:5]
	v_mfma_f32_16x16x32_bf16 v[30:33], v[232:235], v[200:203], v[30:33]
	v_mfma_f32_16x16x32_bf16 v[26:29], v[240:243], v[200:203], v[26:29]
	v_mfma_f32_16x16x32_bf16 v[22:25], v[232:235], v[208:211], v[22:25]
	v_mfma_f32_16x16x32_bf16 v[18:21], v[240:243], v[208:211], v[18:21]
	v_mfma_f32_16x16x32_bf16 v[14:17], v[232:235], v[216:219], v[14:17]
	v_mfma_f32_16x16x32_bf16 v[10:13], v[240:243], v[216:219], v[10:13]
	v_mfma_f32_16x16x32_bf16 v[6:9], v[232:235], v[224:227], v[6:9]
	v_mfma_f32_16x16x32_bf16 v[2:5], v[240:243], v[224:227], v[2:5]
	s_add_i32 s1, s1, 2
	s_add_u32 s10, s10, 0x100
	s_addc_u32 s11, s11, 0
	s_cmp_lt_u32 s1, 12
	s_barrier
	s_cbranch_scc1 .LBB0_171
	v_readfirstlane_b32 s1, v157
	v_lshl_add_u64 v[140:141], v[140:141], 0, s[78:79]
	s_mov_b32 m0, s1
	v_readfirstlane_b32 s1, v175
	ds_read_b128 v[144:147], v167
	ds_read_b128 v[148:151], v167 offset:1024
	ds_read_b128 v[152:155], v167 offset:2048
	ds_read_b128 v[176:179], v167 offset:3072
	ds_read_b128 v[180:183], v168
	ds_read_b128 v[184:187], v168 offset:1024
	ds_read_b128 v[188:191], v169
	ds_read_b128 v[192:195], v169 offset:1024
	ds_read_b128 v[200:203], v170
	ds_read_b128 v[204:207], v170 offset:1024
	ds_read_b128 v[208:211], v171
	ds_read_b128 v[212:215], v171 offset:1024
	global_load_lds_dwordx4 v[140:141], off
	v_lshl_add_u64 v[140:141], v[142:143], 0, s[78:79]
	s_mov_b32 m0, s1
	s_nop 0
	global_load_lds_dwordx4 v[140:141], off
	s_barrier
	s_waitcnt lgkmcnt(0)
	s_setprio 1
	s_waitcnt lgkmcnt(0)
	v_mfma_f32_16x16x32_bf16 v[126:129], v[144:147], v[180:183], v[126:129]
	v_mfma_f32_16x16x32_bf16 v[122:125], v[152:155], v[180:183], v[122:125]
	v_mfma_f32_16x16x32_bf16 v[118:121], v[144:147], v[188:191], v[118:121]
	v_mfma_f32_16x16x32_bf16 v[114:117], v[152:155], v[188:191], v[114:117]
	v_mfma_f32_16x16x32_bf16 v[102:105], v[144:147], v[208:211], v[102:105]
	v_mfma_f32_16x16x32_bf16 v[98:101], v[152:155], v[208:211], v[98:101]
	v_mfma_f32_16x16x32_bf16 v[126:129], v[148:151], v[184:187], v[126:129]
	v_mfma_f32_16x16x32_bf16 v[122:125], v[176:179], v[184:187], v[122:125]
	v_mfma_f32_16x16x32_bf16 v[118:121], v[148:151], v[192:195], v[118:121]
	v_mfma_f32_16x16x32_bf16 v[114:117], v[176:179], v[192:195], v[114:117]
	v_mfma_f32_16x16x32_bf16 v[110:113], v[144:147], v[200:203], v[110:113]
	v_mfma_f32_16x16x32_bf16 v[106:109], v[152:155], v[200:203], v[106:109]
	v_mfma_f32_16x16x32_bf16 v[102:105], v[148:151], v[212:215], v[102:105]
	v_mfma_f32_16x16x32_bf16 v[98:101], v[176:179], v[212:215], v[98:101]
	v_mfma_f32_16x16x32_bf16 v[140:143], v[148:151], v[204:207], v[110:113]
	v_mfma_f32_16x16x32_bf16 v[216:219], v[176:179], v[204:207], v[106:109]
	s_setprio 0
	s_barrier
	s_nop 1
	ds_read_b128 v[106:109], v172
	ds_read_b128 v[110:113], v172 offset:1024
	ds_read_b128 v[220:223], v172 offset:2048
	ds_read_b128 v[224:227], v172 offset:3072
	s_barrier
	s_waitcnt lgkmcnt(0)
	s_setprio 1
	s_waitcnt lgkmcnt(0)
	v_mfma_f32_16x16x32_bf16 v[86:89], v[106:109], v[188:191], v[86:89]
	v_mfma_f32_16x16x32_bf16 v[82:85], v[220:223], v[188:191], v[82:85]
	v_mfma_f32_16x16x32_bf16 v[70:73], v[106:109], v[208:211], v[70:73]
	v_mfma_f32_16x16x32_bf16 v[66:69], v[220:223], v[208:211], v[66:69]
	v_mfma_f32_16x16x32_bf16 v[94:97], v[106:109], v[180:183], v[94:97]
	v_mfma_f32_16x16x32_bf16 v[90:93], v[220:223], v[180:183], v[90:93]
	v_mfma_f32_16x16x32_bf16 v[86:89], v[110:113], v[192:195], v[86:89]
	v_mfma_f32_16x16x32_bf16 v[82:85], v[224:227], v[192:195], v[82:85]
	v_mfma_f32_16x16x32_bf16 v[78:81], v[106:109], v[200:203], v[78:81]
	v_mfma_f32_16x16x32_bf16 v[74:77], v[220:223], v[200:203], v[74:77]
	v_mfma_f32_16x16x32_bf16 v[70:73], v[110:113], v[212:215], v[70:73]
	v_mfma_f32_16x16x32_bf16 v[66:69], v[224:227], v[212:215], v[66:69]
	v_mfma_f32_16x16x32_bf16 v[228:231], v[110:113], v[184:187], v[94:97]
	v_mfma_f32_16x16x32_bf16 v[180:183], v[224:227], v[184:187], v[90:93]
	v_mfma_f32_16x16x32_bf16 v[184:187], v[110:113], v[204:207], v[78:81]
	v_mfma_f32_16x16x32_bf16 v[188:191], v[224:227], v[204:207], v[74:77]
	s_setprio 0
	s_barrier
	s_nop 0
	ds_read_b128 v[74:77], v168 offset:16384
	ds_read_b128 v[78:81], v168 offset:17408
	ds_read_b128 v[90:93], v169 offset:16384
	ds_read_b128 v[94:97], v169 offset:17408
	ds_read_b128 v[192:195], v170 offset:16384
	ds_read_b128 v[200:203], v170 offset:17408
	ds_read_b128 v[204:207], v171 offset:16384
	ds_read_b128 v[208:211], v171 offset:17408
	s_waitcnt vmcnt(4)
	s_barrier
	s_waitcnt lgkmcnt(0)
	s_setprio 1
	s_waitcnt lgkmcnt(0)
	v_mfma_f32_16x16x32_bf16 v[62:65], v[144:147], v[74:77], v[62:65]
	v_mfma_f32_16x16x32_bf16 v[58:61], v[152:155], v[74:77], v[58:61]
	v_mfma_f32_16x16x32_bf16 v[54:57], v[144:147], v[90:93], v[54:57]
	v_mfma_f32_16x16x32_bf16 v[50:53], v[152:155], v[90:93], v[50:53]
	v_mfma_f32_16x16x32_bf16 v[38:41], v[144:147], v[204:207], v[38:41]
	v_mfma_f32_16x16x32_bf16 v[34:37], v[152:155], v[204:207], v[34:37]
	v_mfma_f32_16x16x32_bf16 v[62:65], v[148:151], v[78:81], v[62:65]
	v_mfma_f32_16x16x32_bf16 v[58:61], v[176:179], v[78:81], v[58:61]
	v_mfma_f32_16x16x32_bf16 v[54:57], v[148:151], v[94:97], v[54:57]
	v_mfma_f32_16x16x32_bf16 v[50:53], v[176:179], v[94:97], v[50:53]
	v_mfma_f32_16x16x32_bf16 v[46:49], v[144:147], v[192:195], v[46:49]
	v_mfma_f32_16x16x32_bf16 v[42:45], v[152:155], v[192:195], v[42:45]
	v_mfma_f32_16x16x32_bf16 v[38:41], v[148:151], v[208:211], v[38:41]
	v_mfma_f32_16x16x32_bf16 v[34:37], v[176:179], v[208:211], v[34:37]
	v_mfma_f32_16x16x32_bf16 v[212:215], v[148:151], v[200:203], v[46:49]
	v_mfma_f32_16x16x32_bf16 v[232:235], v[176:179], v[200:203], v[42:45]
	s_setprio 0
	s_setprio 1
	v_mfma_f32_16x16x32_bf16 v[22:25], v[106:109], v[90:93], v[22:25]
	v_mfma_f32_16x16x32_bf16 v[18:21], v[220:223], v[90:93], v[18:21]
	v_mfma_f32_16x16x32_bf16 v[6:9], v[106:109], v[204:207], v[6:9]
	v_mfma_f32_16x16x32_bf16 v[2:5], v[220:223], v[204:207], v[2:5]
	v_mfma_f32_16x16x32_bf16 v[30:33], v[106:109], v[74:77], v[30:33]
	v_mfma_f32_16x16x32_bf16 v[26:29], v[220:223], v[74:77], v[26:29]
	v_mfma_f32_16x16x32_bf16 v[22:25], v[110:113], v[94:97], v[22:25]
	v_mfma_f32_16x16x32_bf16 v[18:21], v[224:227], v[94:97], v[18:21]
	v_mfma_f32_16x16x32_bf16 v[14:17], v[106:109], v[192:195], v[14:17]
	v_mfma_f32_16x16x32_bf16 v[10:13], v[220:223], v[192:195], v[10:13]
	v_mfma_f32_16x16x32_bf16 v[6:9], v[110:113], v[208:211], v[6:9]
	v_mfma_f32_16x16x32_bf16 v[2:5], v[224:227], v[208:211], v[2:5]
	v_mfma_f32_16x16x32_bf16 v[144:147], v[110:113], v[78:81], v[30:33]
	v_mfma_f32_16x16x32_bf16 v[148:151], v[224:227], v[78:81], v[26:29]
	v_mfma_f32_16x16x32_bf16 v[152:155], v[110:113], v[200:203], v[14:17]
	v_mfma_f32_16x16x32_bf16 v[176:179], v[224:227], v[200:203], v[10:13]
	s_setprio 0
	s_barrier
	s_nop 0
	ds_read_b128 v[10:13], v173
	ds_read_b128 v[14:17], v173 offset:1024
	ds_read_b128 v[192:195], v173 offset:2048
	ds_read_b128 v[200:203], v173 offset:3072
	ds_read_b128 v[26:29], v168 offset:32768
	ds_read_b128 v[30:33], v168 offset:33792
	ds_read_b128 v[42:45], v169 offset:32768
	ds_read_b128 v[46:49], v169 offset:33792
	ds_read_b128 v[204:207], v170 offset:32768
	ds_read_b128 v[208:211], v170 offset:33792
	ds_read_b128 v[220:223], v171 offset:32768
	ds_read_b128 v[224:227], v171 offset:33792
	s_waitcnt vmcnt(2)
	s_barrier
	s_waitcnt lgkmcnt(0)
	s_setprio 1
	s_waitcnt lgkmcnt(0)
	v_mfma_f32_16x16x32_bf16 v[74:77], v[10:13], v[26:29], v[126:129]
	v_mfma_f32_16x16x32_bf16 v[126:129], v[14:17], v[30:33], v[74:77]
	v_mfma_f32_16x16x32_bf16 v[74:77], v[192:195], v[26:29], v[122:125]
	v_mfma_f32_16x16x32_bf16 v[122:125], v[200:203], v[30:33], v[74:77]
	v_mfma_f32_16x16x32_bf16 v[74:77], v[10:13], v[42:45], v[118:121]
	v_mfma_f32_16x16x32_bf16 v[110:113], v[14:17], v[46:49], v[74:77]
	v_mfma_f32_16x16x32_bf16 v[74:77], v[192:195], v[42:45], v[114:117]
	v_mfma_f32_16x16x32_bf16 v[106:109], v[200:203], v[46:49], v[74:77]
	v_mfma_f32_16x16x32_bf16 v[74:77], v[10:13], v[204:207], v[140:143]
	v_mfma_f32_16x16x32_bf16 v[94:97], v[14:17], v[208:211], v[74:77]
	v_mfma_f32_16x16x32_bf16 v[74:77], v[192:195], v[204:207], v[216:219]
	v_mfma_f32_16x16x32_bf16 v[90:93], v[200:203], v[208:211], v[74:77]
	v_mfma_f32_16x16x32_bf16 v[74:77], v[10:13], v[220:223], v[102:105]
	v_mfma_f32_16x16x32_bf16 v[78:81], v[14:17], v[224:227], v[74:77]
	v_mfma_f32_16x16x32_bf16 v[74:77], v[192:195], v[220:223], v[98:101]
	v_mfma_f32_16x16x32_bf16 v[74:77], v[200:203], v[224:227], v[74:77]
	s_setprio 0
	s_barrier
	ds_read_b128 v[140:143], v174
	ds_read_b128 v[216:219], v174 offset:1024
	ds_read_b128 v[236:239], v174 offset:2048
	ds_read_b128 v[240:243], v174 offset:3072
	s_waitcnt vmcnt(0)
	s_barrier
	s_waitcnt lgkmcnt(0)
	s_setprio 1
	s_waitcnt lgkmcnt(0)
	v_mfma_f32_16x16x32_bf16 v[98:101], v[140:143], v[26:29], v[228:231]
	v_mfma_f32_16x16x32_bf16 v[26:29], v[236:239], v[26:29], v[180:183]
	v_mfma_f32_16x16x32_bf16 v[114:117], v[240:243], v[30:33], v[26:29]
	v_mfma_f32_16x16x32_bf16 v[26:29], v[140:143], v[42:45], v[86:89]
	v_mfma_f32_16x16x32_bf16 v[102:105], v[216:219], v[46:49], v[26:29]
	v_mfma_f32_16x16x32_bf16 v[26:29], v[236:239], v[42:45], v[82:85]
	v_mfma_f32_16x16x32_bf16 v[118:121], v[216:219], v[30:33], v[98:101]
	v_mfma_f32_16x16x32_bf16 v[98:101], v[240:243], v[46:49], v[26:29]
	v_mfma_f32_16x16x32_bf16 v[26:29], v[140:143], v[204:207], v[184:187]
	v_mfma_f32_16x16x32_bf16 v[86:89], v[216:219], v[208:211], v[26:29]
	v_mfma_f32_16x16x32_bf16 v[26:29], v[236:239], v[204:207], v[188:191]
	v_mfma_f32_16x16x32_bf16 v[82:85], v[240:243], v[208:211], v[26:29]
	v_mfma_f32_16x16x32_bf16 v[26:29], v[140:143], v[220:223], v[70:73]
	v_mfma_f32_16x16x32_bf16 v[70:73], v[216:219], v[224:227], v[26:29]
	v_mfma_f32_16x16x32_bf16 v[26:29], v[236:239], v[220:223], v[66:69]
	v_mfma_f32_16x16x32_bf16 v[66:69], v[240:243], v[224:227], v[26:29]
	s_setprio 0
	s_barrier
	ds_read_b128 v[180:183], v168 offset:49152
	ds_read_b128 v[184:187], v168 offset:50176
	ds_read_b128 v[188:191], v169 offset:49152
	ds_read_b128 v[204:207], v169 offset:50176
	ds_read_b128 v[208:211], v170 offset:49152
	ds_read_b128 v[220:223], v170 offset:50176
	ds_read_b128 v[224:227], v171 offset:49152
	ds_read_b128 v[228:231], v171 offset:50176
	s_barrier
	s_waitcnt lgkmcnt(0)
	s_setprio 1
	s_waitcnt lgkmcnt(0)
	v_mfma_f32_16x16x32_bf16 v[26:29], v[10:13], v[180:183], v[62:65]
	v_mfma_f32_16x16x32_bf16 v[62:65], v[14:17], v[184:187], v[26:29]
	v_mfma_f32_16x16x32_bf16 v[26:29], v[192:195], v[180:183], v[58:61]
	v_mfma_f32_16x16x32_bf16 v[58:61], v[200:203], v[184:187], v[26:29]
	v_mfma_f32_16x16x32_bf16 v[26:29], v[10:13], v[188:191], v[54:57]
	v_mfma_f32_16x16x32_bf16 v[46:49], v[14:17], v[204:207], v[26:29]
	v_mfma_f32_16x16x32_bf16 v[26:29], v[192:195], v[188:191], v[50:53]
	v_mfma_f32_16x16x32_bf16 v[42:45], v[200:203], v[204:207], v[26:29]
	v_mfma_f32_16x16x32_bf16 v[26:29], v[10:13], v[208:211], v[212:215]
	v_mfma_f32_16x16x32_bf16 v[10:13], v[10:13], v[224:227], v[38:41]
	v_mfma_f32_16x16x32_bf16 v[30:33], v[14:17], v[220:223], v[26:29]
	v_mfma_f32_16x16x32_bf16 v[26:29], v[192:195], v[208:211], v[232:235]
	v_mfma_f32_16x16x32_bf16 v[14:17], v[14:17], v[228:231], v[10:13]
	v_mfma_f32_16x16x32_bf16 v[10:13], v[192:195], v[224:227], v[34:37]
	v_mfma_f32_16x16x32_bf16 v[26:29], v[200:203], v[220:223], v[26:29]
	v_mfma_f32_16x16x32_bf16 v[10:13], v[200:203], v[228:231], v[10:13]
	s_setprio 0
	s_setprio 1
	v_mfma_f32_16x16x32_bf16 v[34:37], v[140:143], v[180:183], v[144:147]
	v_mfma_f32_16x16x32_bf16 v[54:57], v[216:219], v[184:187], v[34:37]
	v_mfma_f32_16x16x32_bf16 v[34:37], v[236:239], v[180:183], v[148:151]
	v_mfma_f32_16x16x32_bf16 v[18:21], v[236:239], v[188:191], v[18:21]
	v_mfma_f32_16x16x32_bf16 v[50:53], v[240:243], v[184:187], v[34:37]
	v_mfma_f32_16x16x32_bf16 v[22:25], v[140:143], v[188:191], v[22:25]
	v_mfma_f32_16x16x32_bf16 v[34:37], v[240:243], v[204:207], v[18:21]
	v_mfma_f32_16x16x32_bf16 v[18:21], v[140:143], v[208:211], v[152:155]
	v_mfma_f32_16x16x32_bf16 v[38:41], v[216:219], v[204:207], v[22:25]
	v_mfma_f32_16x16x32_bf16 v[22:25], v[216:219], v[220:223], v[18:21]
	v_mfma_f32_16x16x32_bf16 v[18:21], v[236:239], v[208:211], v[176:179]
	v_mfma_f32_16x16x32_bf16 v[6:9], v[140:143], v[224:227], v[6:9]
	v_mfma_f32_16x16x32_bf16 v[2:5], v[236:239], v[224:227], v[2:5]
	v_mfma_f32_16x16x32_bf16 v[18:21], v[240:243], v[220:223], v[18:21]
	v_mfma_f32_16x16x32_bf16 v[6:9], v[216:219], v[228:231], v[6:9]
	v_mfma_f32_16x16x32_bf16 v[2:5], v[240:243], v[228:231], v[2:5]
	s_setprio 0
	s_barrier
	s_and_saveexec_b64 s[4:5], s[74:75]
	s_cbranch_execz .LBB0_174
	s_barrier

.LBB0_2247:
	ds_read_b128 v[178:181], v162
	ds_read_b128 v[182:185], v162 offset:1024
	ds_read_b128 v[186:189], v162 offset:2048
	ds_read_b128 v[190:193], v162 offset:3072
	v_add_u32_e32 v175, 0xc000, v155
	v_lshl_add_u64 v[244:245], s[36:37], 0, v[148:149]
	v_readfirstlane_b32 s35, v175
	v_lshl_add_u64 v[176:177], v[244:245], 0, s[14:15]
	s_mov_b32 m0, s35
	ds_read_b128 v[194:197], v163
	ds_read_b128 v[200:203], v163 offset:1024
	ds_read_b128 v[204:207], v164
	ds_read_b128 v[208:211], v164 offset:1024
	ds_read_b128 v[212:215], v165
	ds_read_b128 v[216:219], v165 offset:1024
	ds_read_b128 v[220:223], v166
	ds_read_b128 v[224:227], v166 offset:1024
	global_load_lds_dwordx4 v[176:177], off
	v_add_u32_e32 v176, 0xe000, v155
	v_lshl_add_u64 v[246:247], s[36:37], 0, v[150:151]
	v_readfirstlane_b32 s35, v176
	v_lshl_add_u64 v[228:229], v[246:247], 0, s[14:15]
	s_mov_b32 m0, s35
	s_nop 0
	global_load_lds_dwordx4 v[228:229], off
	s_waitcnt lgkmcnt(8)
	s_barrier
	s_waitcnt lgkmcnt(0)
	s_waitcnt lgkmcnt(0)
	v_mfma_f32_16x16x32_bf16 v[126:129], v[178:181], v[194:197], v[126:129]
	v_mfma_f32_16x16x32_bf16 v[122:125], v[186:189], v[194:197], v[122:125]
	v_mfma_f32_16x16x32_bf16 v[118:121], v[178:181], v[204:207], v[118:121]
	v_mfma_f32_16x16x32_bf16 v[114:117], v[186:189], v[204:207], v[114:117]
	v_mfma_f32_16x16x32_bf16 v[110:113], v[178:181], v[212:215], v[110:113]
	v_mfma_f32_16x16x32_bf16 v[106:109], v[186:189], v[212:215], v[106:109]
	v_mfma_f32_16x16x32_bf16 v[102:105], v[178:181], v[220:223], v[102:105]
	v_mfma_f32_16x16x32_bf16 v[98:101], v[186:189], v[220:223], v[98:101]
	v_mfma_f32_16x16x32_bf16 v[126:129], v[182:185], v[200:203], v[126:129]
	v_mfma_f32_16x16x32_bf16 v[122:125], v[190:193], v[200:203], v[122:125]
	v_mfma_f32_16x16x32_bf16 v[118:121], v[182:185], v[208:211], v[118:121]
	v_mfma_f32_16x16x32_bf16 v[114:117], v[190:193], v[208:211], v[114:117]
	v_mfma_f32_16x16x32_bf16 v[110:113], v[182:185], v[216:219], v[110:113]
	v_mfma_f32_16x16x32_bf16 v[106:109], v[190:193], v[216:219], v[106:109]
	v_mfma_f32_16x16x32_bf16 v[102:105], v[182:185], v[224:227], v[102:105]
	v_mfma_f32_16x16x32_bf16 v[98:101], v[190:193], v[224:227], v[98:101]
	s_barrier
	v_lshl_add_u64 v[248:249], s[36:37], 0, v[144:145]
	v_readfirstlane_b32 s35, v153
	v_lshl_add_u64 v[250:251], v[248:249], 0, s[16:17]
	s_mov_b32 m0, s35
	ds_read_b128 v[228:231], v167
	ds_read_b128 v[232:235], v167 offset:1024
	ds_read_b128 v[236:239], v167 offset:2048
	ds_read_b128 v[240:243], v167 offset:3072
	global_load_lds_dwordx4 v[250:251], off
	v_lshl_add_u64 v[250:251], s[36:37], 0, v[146:147]
	v_readfirstlane_b32 s35, v154
	v_lshl_add_u64 v[252:253], v[250:251], 0, s[16:17]
	s_mov_b32 m0, s35
	s_nop 0
	global_load_lds_dwordx4 v[252:253], off
	s_barrier
	s_waitcnt lgkmcnt(0)
	s_waitcnt lgkmcnt(0)
	v_mfma_f32_16x16x32_bf16 v[94:97], v[228:231], v[194:197], v[94:97]
	v_mfma_f32_16x16x32_bf16 v[90:93], v[236:239], v[194:197], v[90:93]
	v_mfma_f32_16x16x32_bf16 v[86:89], v[228:231], v[204:207], v[86:89]
	v_mfma_f32_16x16x32_bf16 v[82:85], v[236:239], v[204:207], v[82:85]
	v_mfma_f32_16x16x32_bf16 v[78:81], v[228:231], v[212:215], v[78:81]
	v_mfma_f32_16x16x32_bf16 v[74:77], v[236:239], v[212:215], v[74:77]
	v_mfma_f32_16x16x32_bf16 v[70:73], v[228:231], v[220:223], v[70:73]
	v_mfma_f32_16x16x32_bf16 v[66:69], v[236:239], v[220:223], v[66:69]
	v_mfma_f32_16x16x32_bf16 v[94:97], v[232:235], v[200:203], v[94:97]
	v_mfma_f32_16x16x32_bf16 v[90:93], v[240:243], v[200:203], v[90:93]
	v_mfma_f32_16x16x32_bf16 v[86:89], v[232:235], v[208:211], v[86:89]
	v_mfma_f32_16x16x32_bf16 v[82:85], v[240:243], v[208:211], v[82:85]
	v_mfma_f32_16x16x32_bf16 v[78:81], v[232:235], v[216:219], v[78:81]
	v_mfma_f32_16x16x32_bf16 v[74:77], v[240:243], v[216:219], v[74:77]
	v_mfma_f32_16x16x32_bf16 v[70:73], v[232:235], v[224:227], v[70:73]
	v_mfma_f32_16x16x32_bf16 v[66:69], v[240:243], v[224:227], v[66:69]
	v_readfirstlane_b32 s35, v155
	v_lshl_add_u64 v[252:253], v[244:245], 0, s[18:19]
	s_mov_b32 m0, s35
	v_readfirstlane_b32 s35, v156
	s_barrier
	ds_read_b128 v[194:197], v163 offset:16384
	ds_read_b128 v[200:203], v163 offset:17408
	ds_read_b128 v[204:207], v164 offset:16384
	ds_read_b128 v[208:211], v164 offset:17408
	ds_read_b128 v[212:215], v165 offset:16384
	ds_read_b128 v[216:219], v165 offset:17408
	ds_read_b128 v[220:223], v166 offset:16384
	ds_read_b128 v[224:227], v166 offset:17408
	global_load_lds_dwordx4 v[252:253], off
	v_lshl_add_u64 v[252:253], v[246:247], 0, s[18:19]
	s_mov_b32 m0, s35
	s_nop 0
	global_load_lds_dwordx4 v[252:253], off
	s_barrier
	s_waitcnt lgkmcnt(0)
	s_waitcnt lgkmcnt(0)
	v_mfma_f32_16x16x32_bf16 v[62:65], v[178:181], v[194:197], v[62:65]
	v_mfma_f32_16x16x32_bf16 v[58:61], v[186:189], v[194:197], v[58:61]
	v_mfma_f32_16x16x32_bf16 v[54:57], v[178:181], v[204:207], v[54:57]
	v_mfma_f32_16x16x32_bf16 v[50:53], v[186:189], v[204:207], v[50:53]
	v_mfma_f32_16x16x32_bf16 v[46:49], v[178:181], v[212:215], v[46:49]
	v_mfma_f32_16x16x32_bf16 v[42:45], v[186:189], v[212:215], v[42:45]
	v_mfma_f32_16x16x32_bf16 v[38:41], v[178:181], v[220:223], v[38:41]
	v_mfma_f32_16x16x32_bf16 v[34:37], v[186:189], v[220:223], v[34:37]
	v_mfma_f32_16x16x32_bf16 v[62:65], v[182:185], v[200:203], v[62:65]
	v_mfma_f32_16x16x32_bf16 v[58:61], v[190:193], v[200:203], v[58:61]
	v_mfma_f32_16x16x32_bf16 v[54:57], v[182:185], v[208:211], v[54:57]
	v_mfma_f32_16x16x32_bf16 v[50:53], v[190:193], v[208:211], v[50:53]
	v_mfma_f32_16x16x32_bf16 v[46:49], v[182:185], v[216:219], v[46:49]
	v_mfma_f32_16x16x32_bf16 v[42:45], v[190:193], v[216:219], v[42:45]
	v_mfma_f32_16x16x32_bf16 v[38:41], v[182:185], v[224:227], v[38:41]
	v_mfma_f32_16x16x32_bf16 v[34:37], v[190:193], v[224:227], v[34:37]
	s_barrier
	v_readfirstlane_b32 s35, v157
	v_lshl_add_u64 v[178:179], v[248:249], 0, s[20:21]
	s_mov_b32 m0, s35
	v_readfirstlane_b32 s35, v158
	global_load_lds_dwordx4 v[178:179], off
	v_lshl_add_u64 v[178:179], v[250:251], 0, s[20:21]
	s_mov_b32 m0, s35
	s_nop 0
	global_load_lds_dwordx4 v[178:179], off
	s_waitcnt vmcnt(6)
	s_barrier
	v_mfma_f32_16x16x32_bf16 v[30:33], v[228:231], v[194:197], v[30:33]
	v_mfma_f32_16x16x32_bf16 v[26:29], v[236:239], v[194:197], v[26:29]
	v_mfma_f32_16x16x32_bf16 v[22:25], v[228:231], v[204:207], v[22:25]
	v_mfma_f32_16x16x32_bf16 v[18:21], v[236:239], v[204:207], v[18:21]
	v_mfma_f32_16x16x32_bf16 v[14:17], v[228:231], v[212:215], v[14:17]
	v_mfma_f32_16x16x32_bf16 v[10:13], v[236:239], v[212:215], v[10:13]
	v_mfma_f32_16x16x32_bf16 v[6:9], v[228:231], v[220:223], v[6:9]
	v_mfma_f32_16x16x32_bf16 v[2:5], v[236:239], v[220:223], v[2:5]
	v_mfma_f32_16x16x32_bf16 v[30:33], v[232:235], v[200:203], v[30:33]
	v_mfma_f32_16x16x32_bf16 v[26:29], v[240:243], v[200:203], v[26:29]
	v_mfma_f32_16x16x32_bf16 v[22:25], v[232:235], v[208:211], v[22:25]
	v_mfma_f32_16x16x32_bf16 v[18:21], v[240:243], v[208:211], v[18:21]
	v_mfma_f32_16x16x32_bf16 v[14:17], v[232:235], v[216:219], v[14:17]
	v_mfma_f32_16x16x32_bf16 v[10:13], v[240:243], v[216:219], v[10:13]
	v_mfma_f32_16x16x32_bf16 v[6:9], v[232:235], v[224:227], v[6:9]
	v_mfma_f32_16x16x32_bf16 v[2:5], v[240:243], v[224:227], v[2:5]
	s_barrier
	ds_read_b128 v[178:181], v168
	ds_read_b128 v[182:185], v168 offset:1024
	ds_read_b128 v[186:189], v168 offset:2048
	ds_read_b128 v[190:193], v168 offset:3072
	v_readfirstlane_b32 s35, v159
	v_lshl_add_u64 v[228:229], v[244:245], 0, s[22:23]
	s_mov_b32 m0, s35
	v_readfirstlane_b32 s35, v160
	ds_read_b128 v[194:197], v163 offset:32768
	ds_read_b128 v[200:203], v163 offset:33792
	ds_read_b128 v[204:207], v164 offset:32768
	ds_read_b128 v[208:211], v164 offset:33792
	ds_read_b128 v[212:215], v165 offset:32768
	ds_read_b128 v[216:219], v165 offset:33792
	ds_read_b128 v[220:223], v166 offset:32768
	ds_read_b128 v[224:227], v166 offset:33792
	global_load_lds_dwordx4 v[228:229], off
	v_lshl_add_u64 v[228:229], v[246:247], 0, s[22:23]
	s_mov_b32 m0, s35
	s_nop 0
	global_load_lds_dwordx4 v[228:229], off
	s_waitcnt lgkmcnt(8)
	s_barrier
	s_waitcnt lgkmcnt(0)
	s_waitcnt lgkmcnt(0)
	v_mfma_f32_16x16x32_bf16 v[126:129], v[178:181], v[194:197], v[126:129]
	v_mfma_f32_16x16x32_bf16 v[122:125], v[186:189], v[194:197], v[122:125]
	v_mfma_f32_16x16x32_bf16 v[118:121], v[178:181], v[204:207], v[118:121]
	v_mfma_f32_16x16x32_bf16 v[114:117], v[186:189], v[204:207], v[114:117]
	v_mfma_f32_16x16x32_bf16 v[110:113], v[178:181], v[212:215], v[110:113]
	v_mfma_f32_16x16x32_bf16 v[106:109], v[186:189], v[212:215], v[106:109]
	v_mfma_f32_16x16x32_bf16 v[102:105], v[178:181], v[220:223], v[102:105]
	v_mfma_f32_16x16x32_bf16 v[98:101], v[186:189], v[220:223], v[98:101]
	v_mfma_f32_16x16x32_bf16 v[126:129], v[182:185], v[200:203], v[126:129]
	v_mfma_f32_16x16x32_bf16 v[122:125], v[190:193], v[200:203], v[122:125]
	v_mfma_f32_16x16x32_bf16 v[118:121], v[182:185], v[208:211], v[118:121]
	v_mfma_f32_16x16x32_bf16 v[114:117], v[190:193], v[208:211], v[114:117]
	v_mfma_f32_16x16x32_bf16 v[110:113], v[182:185], v[216:219], v[110:113]
	v_mfma_f32_16x16x32_bf16 v[106:109], v[190:193], v[216:219], v[106:109]
	v_mfma_f32_16x16x32_bf16 v[102:105], v[182:185], v[224:227], v[102:105]
	v_mfma_f32_16x16x32_bf16 v[98:101], v[190:193], v[224:227], v[98:101]
	s_barrier
	v_readfirstlane_b32 s35, v134
	v_lshl_add_u64 v[252:253], v[248:249], 0, s[24:25]
	s_mov_b32 m0, s35
	v_readfirstlane_b32 s35, v170
	ds_read_b128 v[228:231], v169
	ds_read_b128 v[232:235], v169 offset:1024
	ds_read_b128 v[236:239], v169 offset:2048
	ds_read_b128 v[240:243], v169 offset:3072
	global_load_lds_dwordx4 v[252:253], off
	v_lshl_add_u64 v[252:253], v[250:251], 0, s[24:25]
	s_mov_b32 m0, s35
	s_nop 0
	global_load_lds_dwordx4 v[252:253], off
	s_barrier
	s_waitcnt lgkmcnt(0)
	s_waitcnt lgkmcnt(0)
	v_mfma_f32_16x16x32_bf16 v[94:97], v[228:231], v[194:197], v[94:97]
	v_mfma_f32_16x16x32_bf16 v[90:93], v[236:239], v[194:197], v[90:93]
	v_mfma_f32_16x16x32_bf16 v[86:89], v[228:231], v[204:207], v[86:89]
	v_mfma_f32_16x16x32_bf16 v[82:85], v[236:239], v[204:207], v[82:85]
	v_mfma_f32_16x16x32_bf16 v[78:81], v[228:231], v[212:215], v[78:81]
	v_mfma_f32_16x16x32_bf16 v[74:77], v[236:239], v[212:215], v[74:77]
	v_mfma_f32_16x16x32_bf16 v[70:73], v[228:231], v[220:223], v[70:73]
	v_mfma_f32_16x16x32_bf16 v[66:69], v[236:239], v[220:223], v[66:69]
	v_mfma_f32_16x16x32_bf16 v[94:97], v[232:235], v[200:203], v[94:97]
	v_mfma_f32_16x16x32_bf16 v[90:93], v[240:243], v[200:203], v[90:93]
	v_mfma_f32_16x16x32_bf16 v[86:89], v[232:235], v[208:211], v[86:89]
	v_mfma_f32_16x16x32_bf16 v[82:85], v[240:243], v[208:211], v[82:85]
	v_mfma_f32_16x16x32_bf16 v[78:81], v[232:235], v[216:219], v[78:81]
	v_mfma_f32_16x16x32_bf16 v[74:77], v[240:243], v[216:219], v[74:77]
	v_mfma_f32_16x16x32_bf16 v[70:73], v[232:235], v[224:227], v[70:73]
	v_mfma_f32_16x16x32_bf16 v[66:69], v[240:243], v[224:227], v[66:69]
	v_readfirstlane_b32 s35, v171
	v_lshl_add_u64 v[244:245], v[244:245], 0, s[26:27]
	s_mov_b32 m0, s35
	v_readfirstlane_b32 s35, v172
	s_barrier
	ds_read_b128 v[194:197], v163 offset:49152
	ds_read_b128 v[200:203], v163 offset:50176
	ds_read_b128 v[204:207], v164 offset:49152
	ds_read_b128 v[208:211], v164 offset:50176
	ds_read_b128 v[212:215], v165 offset:49152
	ds_read_b128 v[216:219], v165 offset:50176
	ds_read_b128 v[220:223], v166 offset:49152
	ds_read_b128 v[224:227], v166 offset:50176
	global_load_lds_dwordx4 v[244:245], off
	v_lshl_add_u64 v[244:245], v[246:247], 0, s[26:27]
	s_mov_b32 m0, s35
	s_nop 0
	global_load_lds_dwordx4 v[244:245], off
	s_barrier
	s_waitcnt lgkmcnt(0)
	s_waitcnt lgkmcnt(0)
	v_mfma_f32_16x16x32_bf16 v[62:65], v[178:181], v[194:197], v[62:65]
	v_mfma_f32_16x16x32_bf16 v[58:61], v[186:189], v[194:197], v[58:61]
	v_mfma_f32_16x16x32_bf16 v[54:57], v[178:181], v[204:207], v[54:57]
	v_mfma_f32_16x16x32_bf16 v[50:53], v[186:189], v[204:207], v[50:53]
	v_mfma_f32_16x16x32_bf16 v[46:49], v[178:181], v[212:215], v[46:49]
	v_mfma_f32_16x16x32_bf16 v[42:45], v[186:189], v[212:215], v[42:45]
	v_mfma_f32_16x16x32_bf16 v[38:41], v[178:181], v[220:223], v[38:41]
	v_mfma_f32_16x16x32_bf16 v[34:37], v[186:189], v[220:223], v[34:37]
	v_mfma_f32_16x16x32_bf16 v[62:65], v[182:185], v[200:203], v[62:65]
	v_mfma_f32_16x16x32_bf16 v[58:61], v[190:193], v[200:203], v[58:61]
	v_mfma_f32_16x16x32_bf16 v[54:57], v[182:185], v[208:211], v[54:57]
	v_mfma_f32_16x16x32_bf16 v[50:53], v[190:193], v[208:211], v[50:53]
	v_mfma_f32_16x16x32_bf16 v[46:49], v[182:185], v[216:219], v[46:49]
	v_mfma_f32_16x16x32_bf16 v[42:45], v[190:193], v[216:219], v[42:45]
	v_mfma_f32_16x16x32_bf16 v[38:41], v[182:185], v[224:227], v[38:41]
	v_mfma_f32_16x16x32_bf16 v[34:37], v[190:193], v[224:227], v[34:37]
	s_barrier
	v_readfirstlane_b32 s35, v173
	v_lshl_add_u64 v[178:179], v[248:249], 0, s[28:29]
	s_mov_b32 m0, s35
	v_readfirstlane_b32 s35, v174
	global_load_lds_dwordx4 v[178:179], off
	v_lshl_add_u64 v[178:179], v[250:251], 0, s[28:29]
	s_mov_b32 m0, s35
	s_nop 0
	global_load_lds_dwordx4 v[178:179], off
	s_waitcnt vmcnt(6)
	s_barrier
	v_mfma_f32_16x16x32_bf16 v[30:33], v[228:231], v[194:197], v[30:33]
	v_mfma_f32_16x16x32_bf16 v[26:29], v[236:239], v[194:197], v[26:29]
	v_mfma_f32_16x16x32_bf16 v[22:25], v[228:231], v[204:207], v[22:25]
	v_mfma_f32_16x16x32_bf16 v[18:21], v[236:239], v[204:207], v[18:21]
	v_mfma_f32_16x16x32_bf16 v[14:17], v[228:231], v[212:215], v[14:17]
	v_mfma_f32_16x16x32_bf16 v[10:13], v[236:239], v[212:215], v[10:13]
	v_mfma_f32_16x16x32_bf16 v[6:9], v[228:231], v[220:223], v[6:9]
	v_mfma_f32_16x16x32_bf16 v[2:5], v[236:239], v[220:223], v[2:5]
	v_mfma_f32_16x16x32_bf16 v[30:33], v[232:235], v[200:203], v[30:33]
	v_mfma_f32_16x16x32_bf16 v[26:29], v[240:243], v[200:203], v[26:29]
	v_mfma_f32_16x16x32_bf16 v[22:25], v[232:235], v[208:211], v[22:25]
	v_mfma_f32_16x16x32_bf16 v[18:21], v[240:243], v[208:211], v[18:21]
	v_mfma_f32_16x16x32_bf16 v[14:17], v[232:235], v[216:219], v[14:17]
	v_mfma_f32_16x16x32_bf16 v[10:13], v[240:243], v[216:219], v[10:13]
	v_mfma_f32_16x16x32_bf16 v[6:9], v[232:235], v[224:227], v[6:9]
	v_mfma_f32_16x16x32_bf16 v[2:5], v[240:243], v[224:227], v[2:5]
	s_add_i32 s9, s9, 2
	s_add_u32 s36, s36, 0x100
	s_addc_u32 s37, s37, 0
	s_cmp_lt_u32 s9, 12
	s_barrier
	s_cbranch_scc1 .LBB0_2247
	v_readfirstlane_b32 s9, v175
	v_lshl_add_u64 v[140:141], v[140:141], 0, s[30:31]
	s_mov_b32 m0, s9
	v_readfirstlane_b32 s9, v176
	ds_read_b128 v[144:147], v162
	ds_read_b128 v[148:151], v162 offset:1024
	ds_read_b128 v[170:173], v162 offset:2048
	ds_read_b128 v[178:181], v162 offset:3072
	ds_read_b128 v[182:185], v163
	ds_read_b128 v[186:189], v163 offset:1024
	ds_read_b128 v[190:193], v164
	ds_read_b128 v[194:197], v164 offset:1024
	ds_read_b128 v[200:203], v165
	ds_read_b128 v[204:207], v165 offset:1024
	ds_read_b128 v[208:211], v166
	ds_read_b128 v[212:215], v166 offset:1024
	global_load_lds_dwordx4 v[140:141], off
	v_lshl_add_u64 v[140:141], v[142:143], 0, s[30:31]
	s_mov_b32 m0, s9
	s_nop 0
	global_load_lds_dwordx4 v[140:141], off
	s_barrier
	s_waitcnt lgkmcnt(0)
	s_setprio 1
	s_waitcnt lgkmcnt(0)
	v_mfma_f32_16x16x32_bf16 v[126:129], v[144:147], v[182:185], v[126:129]
	v_mfma_f32_16x16x32_bf16 v[122:125], v[170:173], v[182:185], v[122:125]
	v_mfma_f32_16x16x32_bf16 v[114:117], v[170:173], v[190:193], v[114:117]
	v_mfma_f32_16x16x32_bf16 v[106:109], v[170:173], v[200:203], v[106:109]
	v_mfma_f32_16x16x32_bf16 v[98:101], v[170:173], v[208:211], v[98:101]
	v_mfma_f32_16x16x32_bf16 v[126:129], v[148:151], v[186:189], v[126:129]
	v_mfma_f32_16x16x32_bf16 v[122:125], v[178:181], v[186:189], v[122:125]
	v_mfma_f32_16x16x32_bf16 v[118:121], v[144:147], v[190:193], v[118:121]
	v_mfma_f32_16x16x32_bf16 v[114:117], v[178:181], v[194:197], v[114:117]
	v_mfma_f32_16x16x32_bf16 v[110:113], v[144:147], v[200:203], v[110:113]
	v_mfma_f32_16x16x32_bf16 v[106:109], v[178:181], v[204:207], v[106:109]
	v_mfma_f32_16x16x32_bf16 v[102:105], v[144:147], v[208:211], v[102:105]
	v_mfma_f32_16x16x32_bf16 v[98:101], v[178:181], v[212:215], v[98:101]
	v_mfma_f32_16x16x32_bf16 v[140:143], v[148:151], v[194:197], v[118:121]
	v_mfma_f32_16x16x32_bf16 v[174:177], v[148:151], v[204:207], v[110:113]
	v_mfma_f32_16x16x32_bf16 v[216:219], v[148:151], v[212:215], v[102:105]
	s_setprio 0
	s_barrier
	s_nop 1
	ds_read_b128 v[102:105], v167
	ds_read_b128 v[110:113], v167 offset:1024
	ds_read_b128 v[118:121], v167 offset:2048
	ds_read_b128 v[220:223], v167 offset:3072
	s_barrier
	s_waitcnt lgkmcnt(0)
	s_setprio 1
	s_waitcnt lgkmcnt(0)
	v_mfma_f32_16x16x32_bf16 v[90:93], v[118:121], v[182:185], v[90:93]
	v_mfma_f32_16x16x32_bf16 v[82:85], v[118:121], v[190:193], v[82:85]
	v_mfma_f32_16x16x32_bf16 v[74:77], v[118:121], v[200:203], v[74:77]
	v_mfma_f32_16x16x32_bf16 v[66:69], v[118:121], v[208:211], v[66:69]
	v_mfma_f32_16x16x32_bf16 v[94:97], v[102:105], v[182:185], v[94:97]
	v_mfma_f32_16x16x32_bf16 v[90:93], v[220:223], v[186:189], v[90:93]
	v_mfma_f32_16x16x32_bf16 v[86:89], v[102:105], v[190:193], v[86:89]
	v_mfma_f32_16x16x32_bf16 v[82:85], v[220:223], v[194:197], v[82:85]
	v_mfma_f32_16x16x32_bf16 v[78:81], v[102:105], v[200:203], v[78:81]
	v_mfma_f32_16x16x32_bf16 v[74:77], v[220:223], v[204:207], v[74:77]
	v_mfma_f32_16x16x32_bf16 v[70:73], v[102:105], v[208:211], v[70:73]
	v_mfma_f32_16x16x32_bf16 v[66:69], v[220:223], v[212:215], v[66:69]
	v_mfma_f32_16x16x32_bf16 v[224:227], v[110:113], v[186:189], v[94:97]
	v_mfma_f32_16x16x32_bf16 v[182:185], v[110:113], v[194:197], v[86:89]
	v_mfma_f32_16x16x32_bf16 v[186:189], v[110:113], v[204:207], v[78:81]
	v_mfma_f32_16x16x32_bf16 v[190:193], v[110:113], v[212:215], v[70:73]
	s_setprio 0
	s_barrier
	s_nop 0
	ds_read_b128 v[70:73], v163 offset:16384
	ds_read_b128 v[78:81], v163 offset:17408
	ds_read_b128 v[86:89], v164 offset:16384
	ds_read_b128 v[94:97], v164 offset:17408
	ds_read_b128 v[194:197], v165 offset:16384
	ds_read_b128 v[200:203], v165 offset:17408
	ds_read_b128 v[204:207], v166 offset:16384
	ds_read_b128 v[208:211], v166 offset:17408
	s_waitcnt vmcnt(4)
	s_barrier
	s_waitcnt lgkmcnt(0)
	s_setprio 1
	s_waitcnt lgkmcnt(0)
	v_mfma_f32_16x16x32_bf16 v[62:65], v[144:147], v[70:73], v[62:65]
	v_mfma_f32_16x16x32_bf16 v[58:61], v[170:173], v[70:73], v[58:61]
	v_mfma_f32_16x16x32_bf16 v[54:57], v[144:147], v[86:89], v[54:57]
	v_mfma_f32_16x16x32_bf16 v[50:53], v[170:173], v[86:89], v[50:53]
	v_mfma_f32_16x16x32_bf16 v[38:41], v[144:147], v[204:207], v[38:41]
	v_mfma_f32_16x16x32_bf16 v[34:37], v[170:173], v[204:207], v[34:37]
	v_mfma_f32_16x16x32_bf16 v[62:65], v[148:151], v[78:81], v[62:65]
	v_mfma_f32_16x16x32_bf16 v[58:61], v[178:181], v[78:81], v[58:61]
	v_mfma_f32_16x16x32_bf16 v[54:57], v[148:151], v[94:97], v[54:57]
	v_mfma_f32_16x16x32_bf16 v[50:53], v[178:181], v[94:97], v[50:53]
	v_mfma_f32_16x16x32_bf16 v[46:49], v[144:147], v[194:197], v[46:49]
	v_mfma_f32_16x16x32_bf16 v[42:45], v[170:173], v[194:197], v[42:45]
	v_mfma_f32_16x16x32_bf16 v[38:41], v[148:151], v[208:211], v[38:41]
	v_mfma_f32_16x16x32_bf16 v[34:37], v[178:181], v[208:211], v[34:37]
	v_mfma_f32_16x16x32_bf16 v[212:215], v[148:151], v[200:203], v[46:49]
	v_mfma_f32_16x16x32_bf16 v[228:231], v[178:181], v[200:203], v[42:45]
	s_setprio 0
	s_setprio 1
	v_mfma_f32_16x16x32_bf16 v[22:25], v[102:105], v[86:89], v[22:25]
	v_mfma_f32_16x16x32_bf16 v[18:21], v[118:121], v[86:89], v[18:21]
	v_mfma_f32_16x16x32_bf16 v[6:9], v[102:105], v[204:207], v[6:9]
	v_mfma_f32_16x16x32_bf16 v[2:5], v[118:121], v[204:207], v[2:5]
	v_mfma_f32_16x16x32_bf16 v[30:33], v[102:105], v[70:73], v[30:33]
	v_mfma_f32_16x16x32_bf16 v[26:29], v[118:121], v[70:73], v[26:29]
	v_mfma_f32_16x16x32_bf16 v[22:25], v[110:113], v[94:97], v[22:25]
	v_mfma_f32_16x16x32_bf16 v[18:21], v[220:223], v[94:97], v[18:21]
	v_mfma_f32_16x16x32_bf16 v[14:17], v[102:105], v[194:197], v[14:17]
	v_mfma_f32_16x16x32_bf16 v[10:13], v[118:121], v[194:197], v[10:13]
	v_mfma_f32_16x16x32_bf16 v[6:9], v[110:113], v[208:211], v[6:9]
	v_mfma_f32_16x16x32_bf16 v[2:5], v[220:223], v[208:211], v[2:5]
	v_mfma_f32_16x16x32_bf16 v[144:147], v[110:113], v[78:81], v[30:33]
	v_mfma_f32_16x16x32_bf16 v[148:151], v[220:223], v[78:81], v[26:29]
	v_mfma_f32_16x16x32_bf16 v[170:173], v[110:113], v[200:203], v[14:17]
	v_mfma_f32_16x16x32_bf16 v[178:181], v[220:223], v[200:203], v[10:13]
	s_setprio 0
	s_barrier
	s_nop 0
	ds_read_b128 v[10:13], v168
	ds_read_b128 v[14:17], v168 offset:1024
	ds_read_b128 v[194:197], v168 offset:2048
	ds_read_b128 v[200:203], v168 offset:3072
	ds_read_b128 v[26:29], v163 offset:32768
	ds_read_b128 v[30:33], v163 offset:33792
	ds_read_b128 v[42:45], v164 offset:32768
	ds_read_b128 v[46:49], v164 offset:33792
	ds_read_b128 v[204:207], v165 offset:32768
	ds_read_b128 v[208:211], v165 offset:33792
	ds_read_b128 v[220:223], v166 offset:32768
	ds_read_b128 v[232:235], v166 offset:33792
	s_waitcnt vmcnt(2)
	s_barrier
	s_waitcnt lgkmcnt(0)
	s_setprio 1
	s_waitcnt lgkmcnt(0)
	v_mfma_f32_16x16x32_bf16 v[70:73], v[10:13], v[26:29], v[126:129]
	v_mfma_f32_16x16x32_bf16 v[126:129], v[14:17], v[30:33], v[70:73]
	v_mfma_f32_16x16x32_bf16 v[70:73], v[194:197], v[26:29], v[122:125]
	v_mfma_f32_16x16x32_bf16 v[118:121], v[200:203], v[30:33], v[70:73]
	v_mfma_f32_16x16x32_bf16 v[70:73], v[10:13], v[42:45], v[140:143]
	v_mfma_f32_16x16x32_bf16 v[110:113], v[14:17], v[46:49], v[70:73]
	v_mfma_f32_16x16x32_bf16 v[70:73], v[194:197], v[42:45], v[114:117]
	v_mfma_f32_16x16x32_bf16 v[102:105], v[200:203], v[46:49], v[70:73]
	v_mfma_f32_16x16x32_bf16 v[70:73], v[10:13], v[204:207], v[174:177]
	v_mfma_f32_16x16x32_bf16 v[94:97], v[14:17], v[208:211], v[70:73]
	v_mfma_f32_16x16x32_bf16 v[70:73], v[194:197], v[204:207], v[106:109]
	v_mfma_f32_16x16x32_bf16 v[86:89], v[200:203], v[208:211], v[70:73]
	v_mfma_f32_16x16x32_bf16 v[70:73], v[10:13], v[220:223], v[216:219]
	v_mfma_f32_16x16x32_bf16 v[78:81], v[14:17], v[232:235], v[70:73]
	v_mfma_f32_16x16x32_bf16 v[70:73], v[194:197], v[220:223], v[98:101]
	v_mfma_f32_16x16x32_bf16 v[70:73], v[200:203], v[232:235], v[70:73]
	s_setprio 0
	s_barrier
	ds_read_b128 v[140:143], v169
	ds_read_b128 v[174:177], v169 offset:1024
	ds_read_b128 v[216:219], v169 offset:2048
	ds_read_b128 v[236:239], v169 offset:3072
	s_waitcnt vmcnt(0)
	s_barrier
	s_waitcnt lgkmcnt(0)
	s_setprio 1
	s_waitcnt lgkmcnt(0)
	v_mfma_f32_16x16x32_bf16 v[98:101], v[140:143], v[26:29], v[224:227]
	v_mfma_f32_16x16x32_bf16 v[26:29], v[216:219], v[26:29], v[90:93]
	v_mfma_f32_16x16x32_bf16 v[114:117], v[236:239], v[30:33], v[26:29]
	v_mfma_f32_16x16x32_bf16 v[26:29], v[140:143], v[42:45], v[182:185]
	v_mfma_f32_16x16x32_bf16 v[106:109], v[174:177], v[46:49], v[26:29]
	v_mfma_f32_16x16x32_bf16 v[26:29], v[216:219], v[42:45], v[82:85]
	v_mfma_f32_16x16x32_bf16 v[122:125], v[174:177], v[30:33], v[98:101]
	v_mfma_f32_16x16x32_bf16 v[98:101], v[236:239], v[46:49], v[26:29]
	v_mfma_f32_16x16x32_bf16 v[26:29], v[140:143], v[204:207], v[186:189]
	v_mfma_f32_16x16x32_bf16 v[90:93], v[174:177], v[208:211], v[26:29]
	v_mfma_f32_16x16x32_bf16 v[26:29], v[216:219], v[204:207], v[74:77]
	v_mfma_f32_16x16x32_bf16 v[82:85], v[236:239], v[208:211], v[26:29]
	v_mfma_f32_16x16x32_bf16 v[26:29], v[140:143], v[220:223], v[190:193]
	v_mfma_f32_16x16x32_bf16 v[74:77], v[174:177], v[232:235], v[26:29]
	v_mfma_f32_16x16x32_bf16 v[26:29], v[216:219], v[220:223], v[66:69]
	v_mfma_f32_16x16x32_bf16 v[66:69], v[236:239], v[232:235], v[26:29]
	s_setprio 0
	s_barrier
	ds_read_b128 v[182:185], v163 offset:49152
	ds_read_b128 v[186:189], v163 offset:50176
	ds_read_b128 v[190:193], v164 offset:49152
	ds_read_b128 v[204:207], v164 offset:50176
	ds_read_b128 v[208:211], v165 offset:49152
	ds_read_b128 v[220:223], v165 offset:50176
	ds_read_b128 v[224:227], v166 offset:49152
	ds_read_b128 v[232:235], v166 offset:50176
	s_barrier
	s_waitcnt lgkmcnt(0)
	s_setprio 1
	s_waitcnt lgkmcnt(0)
	v_mfma_f32_16x16x32_bf16 v[26:29], v[10:13], v[182:185], v[62:65]
	v_mfma_f32_16x16x32_bf16 v[62:65], v[14:17], v[186:189], v[26:29]
	v_mfma_f32_16x16x32_bf16 v[26:29], v[194:197], v[182:185], v[58:61]
	v_mfma_f32_16x16x32_bf16 v[58:61], v[200:203], v[186:189], v[26:29]
	v_mfma_f32_16x16x32_bf16 v[26:29], v[10:13], v[190:193], v[54:57]
	v_mfma_f32_16x16x32_bf16 v[46:49], v[14:17], v[204:207], v[26:29]
	v_mfma_f32_16x16x32_bf16 v[26:29], v[194:197], v[190:193], v[50:53]
	v_mfma_f32_16x16x32_bf16 v[42:45], v[200:203], v[204:207], v[26:29]
	v_mfma_f32_16x16x32_bf16 v[26:29], v[10:13], v[208:211], v[212:215]
	v_mfma_f32_16x16x32_bf16 v[10:13], v[10:13], v[224:227], v[38:41]
	v_mfma_f32_16x16x32_bf16 v[30:33], v[14:17], v[220:223], v[26:29]
	v_mfma_f32_16x16x32_bf16 v[26:29], v[194:197], v[208:211], v[228:231]
	v_mfma_f32_16x16x32_bf16 v[14:17], v[14:17], v[232:235], v[10:13]
	v_mfma_f32_16x16x32_bf16 v[10:13], v[194:197], v[224:227], v[34:37]
	v_mfma_f32_16x16x32_bf16 v[26:29], v[200:203], v[220:223], v[26:29]
	v_mfma_f32_16x16x32_bf16 v[10:13], v[200:203], v[232:235], v[10:13]
	s_setprio 0
	s_setprio 1
	v_mfma_f32_16x16x32_bf16 v[34:37], v[140:143], v[182:185], v[144:147]
	v_mfma_f32_16x16x32_bf16 v[54:57], v[174:177], v[186:189], v[34:37]
	v_mfma_f32_16x16x32_bf16 v[34:37], v[216:219], v[182:185], v[148:151]
	v_mfma_f32_16x16x32_bf16 v[18:21], v[216:219], v[190:193], v[18:21]
	v_mfma_f32_16x16x32_bf16 v[50:53], v[236:239], v[186:189], v[34:37]
	v_mfma_f32_16x16x32_bf16 v[22:25], v[140:143], v[190:193], v[22:25]
	v_mfma_f32_16x16x32_bf16 v[34:37], v[236:239], v[204:207], v[18:21]
	v_mfma_f32_16x16x32_bf16 v[18:21], v[140:143], v[208:211], v[170:173]
	v_mfma_f32_16x16x32_bf16 v[38:41], v[174:177], v[204:207], v[22:25]
	v_mfma_f32_16x16x32_bf16 v[22:25], v[174:177], v[220:223], v[18:21]
	v_mfma_f32_16x16x32_bf16 v[18:21], v[216:219], v[208:211], v[178:181]
	v_mfma_f32_16x16x32_bf16 v[6:9], v[140:143], v[224:227], v[6:9]
	v_mfma_f32_16x16x32_bf16 v[2:5], v[216:219], v[224:227], v[2:5]
	v_mfma_f32_16x16x32_bf16 v[18:21], v[236:239], v[220:223], v[18:21]
	v_mfma_f32_16x16x32_bf16 v[6:9], v[174:177], v[232:235], v[6:9]
	v_mfma_f32_16x16x32_bf16 v[2:5], v[236:239], v[232:235], v[2:5]
	s_setprio 0
	s_barrier
	s_and_saveexec_b64 s[36:37], s[6:7]
	v_readlane_b32 s64, v254, 29
	v_readlane_b32 s65, v254, 30
	v_readlane_b32 s66, v254, 31
	v_readlane_b32 s67, v254, 32
	v_readlane_b32 s68, v254, 33
	v_readlane_b32 s69, v254, 34
	v_readlane_b32 s70, v254, 35
	v_readlane_b32 s71, v254, 36
	v_readlane_b32 s72, v254, 37
	v_readlane_b32 s73, v254, 38
	v_readlane_b32 s74, v254, 39
	v_readlane_b32 s75, v254, 40
	v_readlane_b32 s76, v254, 41
	v_readlane_b32 s77, v254, 42
	v_readlane_b32 s78, v254, 43
	v_readlane_b32 s79, v254, 44
	s_cbranch_execz .LBB0_2250
	s_barrier

.LBB0_2580:
	ds_read_b128 v[176:179], v168
	ds_read_b128 v[180:183], v168 offset:1024
	ds_read_b128 v[184:187], v168 offset:2048
	ds_read_b128 v[188:191], v168 offset:3072
	v_add_u32_e32 v161, 0xc000, v149
	v_lshl_add_u64 v[164:165], s[36:37], 0, v[144:145]
	v_readfirstlane_b32 s39, v161
	v_lshl_add_u64 v[162:163], v[164:165], 0, s[16:17]
	s_mov_b32 m0, s39
	ds_read_b128 v[192:195], v169
	ds_read_b128 v[200:203], v169 offset:1024
	ds_read_b128 v[204:207], v170
	ds_read_b128 v[208:211], v170 offset:1024
	ds_read_b128 v[212:215], v171
	ds_read_b128 v[216:219], v171 offset:1024
	ds_read_b128 v[220:223], v172
	ds_read_b128 v[224:227], v172 offset:1024
	global_load_lds_dwordx4 v[162:163], off
	v_add_u32_e32 v162, 0xe000, v149
	v_lshl_add_u64 v[196:197], s[36:37], 0, v[146:147]
	v_readfirstlane_b32 s39, v162
	v_lshl_add_u64 v[228:229], v[196:197], 0, s[16:17]
	s_mov_b32 m0, s39
	s_nop 0
	global_load_lds_dwordx4 v[228:229], off
	s_waitcnt lgkmcnt(8)
	s_barrier
	s_waitcnt lgkmcnt(0)
	s_waitcnt lgkmcnt(0)
	v_mfma_f32_16x16x32_bf16 v[126:129], v[176:179], v[192:195], v[126:129]
	v_mfma_f32_16x16x32_bf16 v[122:125], v[184:187], v[192:195], v[122:125]
	v_mfma_f32_16x16x32_bf16 v[118:121], v[176:179], v[204:207], v[118:121]
	v_mfma_f32_16x16x32_bf16 v[114:117], v[184:187], v[204:207], v[114:117]
	v_mfma_f32_16x16x32_bf16 v[110:113], v[176:179], v[212:215], v[110:113]
	v_mfma_f32_16x16x32_bf16 v[106:109], v[184:187], v[212:215], v[106:109]
	v_mfma_f32_16x16x32_bf16 v[102:105], v[176:179], v[220:223], v[102:105]
	v_mfma_f32_16x16x32_bf16 v[98:101], v[184:187], v[220:223], v[98:101]
	v_mfma_f32_16x16x32_bf16 v[126:129], v[180:183], v[200:203], v[126:129]
	v_mfma_f32_16x16x32_bf16 v[122:125], v[188:191], v[200:203], v[122:125]
	v_mfma_f32_16x16x32_bf16 v[118:121], v[180:183], v[208:211], v[118:121]
	v_mfma_f32_16x16x32_bf16 v[114:117], v[188:191], v[208:211], v[114:117]
	v_mfma_f32_16x16x32_bf16 v[110:113], v[180:183], v[216:219], v[110:113]
	v_mfma_f32_16x16x32_bf16 v[106:109], v[188:191], v[216:219], v[106:109]
	v_mfma_f32_16x16x32_bf16 v[102:105], v[180:183], v[224:227], v[102:105]
	v_mfma_f32_16x16x32_bf16 v[98:101], v[188:191], v[224:227], v[98:101]
	s_barrier
	v_lshl_add_u64 v[244:245], s[36:37], 0, v[140:141]
	v_readfirstlane_b32 s39, v134
	v_lshl_add_u64 v[246:247], v[244:245], 0, s[18:19]
	s_mov_b32 m0, s39
	ds_read_b128 v[228:231], v173
	ds_read_b128 v[232:235], v173 offset:1024
	ds_read_b128 v[236:239], v173 offset:2048
	ds_read_b128 v[240:243], v173 offset:3072
	global_load_lds_dwordx4 v[246:247], off
	v_lshl_add_u64 v[246:247], s[36:37], 0, v[142:143]
	v_readfirstlane_b32 s39, v148
	v_lshl_add_u64 v[248:249], v[246:247], 0, s[18:19]
	s_mov_b32 m0, s39
	s_nop 0
	global_load_lds_dwordx4 v[248:249], off
	s_barrier
	s_waitcnt lgkmcnt(0)
	s_waitcnt lgkmcnt(0)
	v_mfma_f32_16x16x32_bf16 v[94:97], v[228:231], v[192:195], v[94:97]
	v_mfma_f32_16x16x32_bf16 v[90:93], v[236:239], v[192:195], v[90:93]
	v_mfma_f32_16x16x32_bf16 v[86:89], v[228:231], v[204:207], v[86:89]
	v_mfma_f32_16x16x32_bf16 v[82:85], v[236:239], v[204:207], v[82:85]
	v_mfma_f32_16x16x32_bf16 v[78:81], v[228:231], v[212:215], v[78:81]
	v_mfma_f32_16x16x32_bf16 v[74:77], v[236:239], v[212:215], v[74:77]
	v_mfma_f32_16x16x32_bf16 v[70:73], v[228:231], v[220:223], v[70:73]
	v_mfma_f32_16x16x32_bf16 v[66:69], v[236:239], v[220:223], v[66:69]
	v_mfma_f32_16x16x32_bf16 v[94:97], v[232:235], v[200:203], v[94:97]
	v_mfma_f32_16x16x32_bf16 v[90:93], v[240:243], v[200:203], v[90:93]
	v_mfma_f32_16x16x32_bf16 v[86:89], v[232:235], v[208:211], v[86:89]
	v_mfma_f32_16x16x32_bf16 v[82:85], v[240:243], v[208:211], v[82:85]
	v_mfma_f32_16x16x32_bf16 v[78:81], v[232:235], v[216:219], v[78:81]
	v_mfma_f32_16x16x32_bf16 v[74:77], v[240:243], v[216:219], v[74:77]
	v_mfma_f32_16x16x32_bf16 v[70:73], v[232:235], v[224:227], v[70:73]
	v_mfma_f32_16x16x32_bf16 v[66:69], v[240:243], v[224:227], v[66:69]
	v_readfirstlane_b32 s39, v149
	v_lshl_add_u64 v[248:249], v[164:165], 0, s[20:21]
	s_mov_b32 m0, s39
	v_readfirstlane_b32 s39, v150
	s_barrier
	ds_read_b128 v[192:195], v169 offset:16384
	ds_read_b128 v[200:203], v169 offset:17408
	ds_read_b128 v[204:207], v170 offset:16384
	ds_read_b128 v[208:211], v170 offset:17408
	ds_read_b128 v[212:215], v171 offset:16384
	ds_read_b128 v[216:219], v171 offset:17408
	ds_read_b128 v[220:223], v172 offset:16384
	ds_read_b128 v[224:227], v172 offset:17408
	global_load_lds_dwordx4 v[248:249], off
	v_lshl_add_u64 v[248:249], v[196:197], 0, s[20:21]
	s_mov_b32 m0, s39
	s_nop 0
	global_load_lds_dwordx4 v[248:249], off
	s_barrier
	s_waitcnt lgkmcnt(0)
	s_waitcnt lgkmcnt(0)
	v_mfma_f32_16x16x32_bf16 v[62:65], v[176:179], v[192:195], v[62:65]
	v_mfma_f32_16x16x32_bf16 v[58:61], v[184:187], v[192:195], v[58:61]
	v_mfma_f32_16x16x32_bf16 v[54:57], v[176:179], v[204:207], v[54:57]
	v_mfma_f32_16x16x32_bf16 v[50:53], v[184:187], v[204:207], v[50:53]
	v_mfma_f32_16x16x32_bf16 v[46:49], v[176:179], v[212:215], v[46:49]
	v_mfma_f32_16x16x32_bf16 v[42:45], v[184:187], v[212:215], v[42:45]
	v_mfma_f32_16x16x32_bf16 v[38:41], v[176:179], v[220:223], v[38:41]
	v_mfma_f32_16x16x32_bf16 v[34:37], v[184:187], v[220:223], v[34:37]
	v_mfma_f32_16x16x32_bf16 v[62:65], v[180:183], v[200:203], v[62:65]
	v_mfma_f32_16x16x32_bf16 v[58:61], v[188:191], v[200:203], v[58:61]
	v_mfma_f32_16x16x32_bf16 v[54:57], v[180:183], v[208:211], v[54:57]
	v_mfma_f32_16x16x32_bf16 v[50:53], v[188:191], v[208:211], v[50:53]
	v_mfma_f32_16x16x32_bf16 v[46:49], v[180:183], v[216:219], v[46:49]
	v_mfma_f32_16x16x32_bf16 v[42:45], v[188:191], v[216:219], v[42:45]
	v_mfma_f32_16x16x32_bf16 v[38:41], v[180:183], v[224:227], v[38:41]
	v_mfma_f32_16x16x32_bf16 v[34:37], v[188:191], v[224:227], v[34:37]
	s_barrier
	v_readfirstlane_b32 s39, v151
	v_lshl_add_u64 v[176:177], v[244:245], 0, s[22:23]
	s_mov_b32 m0, s39
	v_readfirstlane_b32 s39, v152
	global_load_lds_dwordx4 v[176:177], off
	v_lshl_add_u64 v[176:177], v[246:247], 0, s[22:23]
	s_mov_b32 m0, s39
	s_nop 0
	global_load_lds_dwordx4 v[176:177], off
	s_waitcnt vmcnt(6)
	s_barrier
	v_mfma_f32_16x16x32_bf16 v[30:33], v[228:231], v[192:195], v[30:33]
	v_mfma_f32_16x16x32_bf16 v[26:29], v[236:239], v[192:195], v[26:29]
	v_mfma_f32_16x16x32_bf16 v[22:25], v[228:231], v[204:207], v[22:25]
	v_mfma_f32_16x16x32_bf16 v[18:21], v[236:239], v[204:207], v[18:21]
	v_mfma_f32_16x16x32_bf16 v[14:17], v[228:231], v[212:215], v[14:17]
	v_mfma_f32_16x16x32_bf16 v[10:13], v[236:239], v[212:215], v[10:13]
	v_mfma_f32_16x16x32_bf16 v[6:9], v[228:231], v[220:223], v[6:9]
	v_mfma_f32_16x16x32_bf16 v[2:5], v[236:239], v[220:223], v[2:5]
	v_mfma_f32_16x16x32_bf16 v[30:33], v[232:235], v[200:203], v[30:33]
	v_mfma_f32_16x16x32_bf16 v[26:29], v[240:243], v[200:203], v[26:29]
	v_mfma_f32_16x16x32_bf16 v[22:25], v[232:235], v[208:211], v[22:25]
	v_mfma_f32_16x16x32_bf16 v[18:21], v[240:243], v[208:211], v[18:21]
	v_mfma_f32_16x16x32_bf16 v[14:17], v[232:235], v[216:219], v[14:17]
	v_mfma_f32_16x16x32_bf16 v[10:13], v[240:243], v[216:219], v[10:13]
	v_mfma_f32_16x16x32_bf16 v[6:9], v[232:235], v[224:227], v[6:9]
	v_mfma_f32_16x16x32_bf16 v[2:5], v[240:243], v[224:227], v[2:5]
	s_barrier
	ds_read_b128 v[176:179], v174
	ds_read_b128 v[180:183], v174 offset:1024
	ds_read_b128 v[184:187], v174 offset:2048
	ds_read_b128 v[188:191], v174 offset:3072
	v_readfirstlane_b32 s39, v153
	v_lshl_add_u64 v[228:229], v[164:165], 0, s[24:25]
	s_mov_b32 m0, s39
	v_readfirstlane_b32 s39, v154
	ds_read_b128 v[192:195], v169 offset:32768
	ds_read_b128 v[200:203], v169 offset:33792
	ds_read_b128 v[204:207], v170 offset:32768
	ds_read_b128 v[208:211], v170 offset:33792
	ds_read_b128 v[212:215], v171 offset:32768
	ds_read_b128 v[216:219], v171 offset:33792
	ds_read_b128 v[220:223], v172 offset:32768
	ds_read_b128 v[224:227], v172 offset:33792
	global_load_lds_dwordx4 v[228:229], off
	v_lshl_add_u64 v[228:229], v[196:197], 0, s[24:25]
	s_mov_b32 m0, s39
	s_nop 0
	global_load_lds_dwordx4 v[228:229], off
	s_waitcnt lgkmcnt(8)
	s_barrier
	s_waitcnt lgkmcnt(0)
	s_waitcnt lgkmcnt(0)
	v_mfma_f32_16x16x32_bf16 v[126:129], v[176:179], v[192:195], v[126:129]
	v_mfma_f32_16x16x32_bf16 v[122:125], v[184:187], v[192:195], v[122:125]
	v_mfma_f32_16x16x32_bf16 v[118:121], v[176:179], v[204:207], v[118:121]
	v_mfma_f32_16x16x32_bf16 v[114:117], v[184:187], v[204:207], v[114:117]
	v_mfma_f32_16x16x32_bf16 v[110:113], v[176:179], v[212:215], v[110:113]
	v_mfma_f32_16x16x32_bf16 v[106:109], v[184:187], v[212:215], v[106:109]
	v_mfma_f32_16x16x32_bf16 v[102:105], v[176:179], v[220:223], v[102:105]
	v_mfma_f32_16x16x32_bf16 v[98:101], v[184:187], v[220:223], v[98:101]
	v_mfma_f32_16x16x32_bf16 v[126:129], v[180:183], v[200:203], v[126:129]
	v_mfma_f32_16x16x32_bf16 v[122:125], v[188:191], v[200:203], v[122:125]
	v_mfma_f32_16x16x32_bf16 v[118:121], v[180:183], v[208:211], v[118:121]
	v_mfma_f32_16x16x32_bf16 v[114:117], v[188:191], v[208:211], v[114:117]
	v_mfma_f32_16x16x32_bf16 v[110:113], v[180:183], v[216:219], v[110:113]
	v_mfma_f32_16x16x32_bf16 v[106:109], v[188:191], v[216:219], v[106:109]
	v_mfma_f32_16x16x32_bf16 v[102:105], v[180:183], v[224:227], v[102:105]
	v_mfma_f32_16x16x32_bf16 v[98:101], v[188:191], v[224:227], v[98:101]
	s_barrier
	v_readfirstlane_b32 s39, v155
	v_lshl_add_u64 v[248:249], v[244:245], 0, s[26:27]
	s_mov_b32 m0, s39
	v_readfirstlane_b32 s39, v156
	ds_read_b128 v[228:231], v175
	ds_read_b128 v[232:235], v175 offset:1024
	ds_read_b128 v[236:239], v175 offset:2048
	ds_read_b128 v[240:243], v175 offset:3072
	global_load_lds_dwordx4 v[248:249], off
	v_lshl_add_u64 v[248:249], v[246:247], 0, s[26:27]
	s_mov_b32 m0, s39
	s_nop 0
	global_load_lds_dwordx4 v[248:249], off
	s_barrier
	s_waitcnt lgkmcnt(0)
	s_waitcnt lgkmcnt(0)
	v_mfma_f32_16x16x32_bf16 v[94:97], v[228:231], v[192:195], v[94:97]
	v_mfma_f32_16x16x32_bf16 v[90:93], v[236:239], v[192:195], v[90:93]
	v_mfma_f32_16x16x32_bf16 v[86:89], v[228:231], v[204:207], v[86:89]
	v_mfma_f32_16x16x32_bf16 v[82:85], v[236:239], v[204:207], v[82:85]
	v_mfma_f32_16x16x32_bf16 v[78:81], v[228:231], v[212:215], v[78:81]
	v_mfma_f32_16x16x32_bf16 v[74:77], v[236:239], v[212:215], v[74:77]
	v_mfma_f32_16x16x32_bf16 v[70:73], v[228:231], v[220:223], v[70:73]
	v_mfma_f32_16x16x32_bf16 v[66:69], v[236:239], v[220:223], v[66:69]
	v_mfma_f32_16x16x32_bf16 v[94:97], v[232:235], v[200:203], v[94:97]
	v_mfma_f32_16x16x32_bf16 v[90:93], v[240:243], v[200:203], v[90:93]
	v_mfma_f32_16x16x32_bf16 v[86:89], v[232:235], v[208:211], v[86:89]
	v_mfma_f32_16x16x32_bf16 v[82:85], v[240:243], v[208:211], v[82:85]
	v_mfma_f32_16x16x32_bf16 v[78:81], v[232:235], v[216:219], v[78:81]
	v_mfma_f32_16x16x32_bf16 v[74:77], v[240:243], v[216:219], v[74:77]
	v_mfma_f32_16x16x32_bf16 v[70:73], v[232:235], v[224:227], v[70:73]
	v_mfma_f32_16x16x32_bf16 v[66:69], v[240:243], v[224:227], v[66:69]
	v_readfirstlane_b32 s39, v157
	v_lshl_add_u64 v[164:165], v[164:165], 0, s[28:29]
	s_mov_b32 m0, s39
	v_readfirstlane_b32 s39, v158
	s_barrier
	ds_read_b128 v[192:195], v169 offset:49152
	ds_read_b128 v[200:203], v169 offset:50176
	ds_read_b128 v[204:207], v170 offset:49152
	ds_read_b128 v[208:211], v170 offset:50176
	ds_read_b128 v[212:215], v171 offset:49152
	ds_read_b128 v[216:219], v171 offset:50176
	ds_read_b128 v[220:223], v172 offset:49152
	ds_read_b128 v[224:227], v172 offset:50176
	global_load_lds_dwordx4 v[164:165], off
	v_lshl_add_u64 v[164:165], v[196:197], 0, s[28:29]
	s_mov_b32 m0, s39
	s_nop 0
	global_load_lds_dwordx4 v[164:165], off
	s_barrier
	s_waitcnt lgkmcnt(0)
	s_waitcnt lgkmcnt(0)
	v_mfma_f32_16x16x32_bf16 v[62:65], v[176:179], v[192:195], v[62:65]
	v_mfma_f32_16x16x32_bf16 v[58:61], v[184:187], v[192:195], v[58:61]
	v_mfma_f32_16x16x32_bf16 v[54:57], v[176:179], v[204:207], v[54:57]
	v_mfma_f32_16x16x32_bf16 v[50:53], v[184:187], v[204:207], v[50:53]
	v_mfma_f32_16x16x32_bf16 v[46:49], v[176:179], v[212:215], v[46:49]
	v_mfma_f32_16x16x32_bf16 v[42:45], v[184:187], v[212:215], v[42:45]
	v_mfma_f32_16x16x32_bf16 v[38:41], v[176:179], v[220:223], v[38:41]
	v_mfma_f32_16x16x32_bf16 v[34:37], v[184:187], v[220:223], v[34:37]
	v_mfma_f32_16x16x32_bf16 v[62:65], v[180:183], v[200:203], v[62:65]
	v_mfma_f32_16x16x32_bf16 v[58:61], v[188:191], v[200:203], v[58:61]
	v_mfma_f32_16x16x32_bf16 v[54:57], v[180:183], v[208:211], v[54:57]
	v_mfma_f32_16x16x32_bf16 v[50:53], v[188:191], v[208:211], v[50:53]
	v_mfma_f32_16x16x32_bf16 v[46:49], v[180:183], v[216:219], v[46:49]
	v_mfma_f32_16x16x32_bf16 v[42:45], v[188:191], v[216:219], v[42:45]
	v_mfma_f32_16x16x32_bf16 v[38:41], v[180:183], v[224:227], v[38:41]
	v_mfma_f32_16x16x32_bf16 v[34:37], v[188:191], v[224:227], v[34:37]
	s_barrier
	v_readfirstlane_b32 s39, v159
	v_lshl_add_u64 v[164:165], v[244:245], 0, s[30:31]
	s_mov_b32 m0, s39
	v_readfirstlane_b32 s39, v160
	global_load_lds_dwordx4 v[164:165], off
	v_lshl_add_u64 v[164:165], v[246:247], 0, s[30:31]
	s_mov_b32 m0, s39
	s_nop 0
	global_load_lds_dwordx4 v[164:165], off
	s_waitcnt vmcnt(6)
	s_barrier
	v_mfma_f32_16x16x32_bf16 v[30:33], v[228:231], v[192:195], v[30:33]
	v_mfma_f32_16x16x32_bf16 v[26:29], v[236:239], v[192:195], v[26:29]
	v_mfma_f32_16x16x32_bf16 v[22:25], v[228:231], v[204:207], v[22:25]
	v_mfma_f32_16x16x32_bf16 v[18:21], v[236:239], v[204:207], v[18:21]
	v_mfma_f32_16x16x32_bf16 v[14:17], v[228:231], v[212:215], v[14:17]
	v_mfma_f32_16x16x32_bf16 v[10:13], v[236:239], v[212:215], v[10:13]
	v_mfma_f32_16x16x32_bf16 v[6:9], v[228:231], v[220:223], v[6:9]
	v_mfma_f32_16x16x32_bf16 v[2:5], v[236:239], v[220:223], v[2:5]
	v_mfma_f32_16x16x32_bf16 v[30:33], v[232:235], v[200:203], v[30:33]
	v_mfma_f32_16x16x32_bf16 v[26:29], v[240:243], v[200:203], v[26:29]
	v_mfma_f32_16x16x32_bf16 v[22:25], v[232:235], v[208:211], v[22:25]
	v_mfma_f32_16x16x32_bf16 v[18:21], v[240:243], v[208:211], v[18:21]
	v_mfma_f32_16x16x32_bf16 v[14:17], v[232:235], v[216:219], v[14:17]
	v_mfma_f32_16x16x32_bf16 v[10:13], v[240:243], v[216:219], v[10:13]
	v_mfma_f32_16x16x32_bf16 v[6:9], v[232:235], v[224:227], v[6:9]
	v_mfma_f32_16x16x32_bf16 v[2:5], v[240:243], v[224:227], v[2:5]
	s_add_i32 s38, s38, 2
	s_add_u32 s36, s36, 0x100
	s_addc_u32 s37, s37, 0
	s_cmp_lt_u32 s38, 40
	s_barrier
	s_cbranch_scc1 .LBB0_2580
	s_add_u32 s6, s6, 0x1580
	s_addc_u32 s7, s7, 0
	v_readfirstlane_b32 s36, v161
	v_lshl_add_u64 v[164:165], s[6:7], 0, v[132:133]
	s_mov_b32 m0, s36
	v_lshl_add_u64 v[160:161], s[6:7], 0, v[130:131]
	v_readfirstlane_b32 s6, v162
	ds_read_b128 v[140:143], v168
	ds_read_b128 v[144:147], v168 offset:1024
	ds_read_b128 v[148:151], v168 offset:2048
	ds_read_b128 v[152:155], v168 offset:3072
	ds_read_b128 v[156:159], v169
	ds_read_b128 v[176:179], v169 offset:1024
	ds_read_b128 v[180:183], v170
	ds_read_b128 v[184:187], v170 offset:1024
	ds_read_b128 v[188:191], v171
	ds_read_b128 v[192:195], v171 offset:1024
	ds_read_b128 v[200:203], v172
	ds_read_b128 v[204:207], v172 offset:1024
	global_load_lds_dwordx4 v[164:165], off
	s_mov_b32 m0, s6
	s_nop 0
	global_load_lds_dwordx4 v[160:161], off
	s_barrier
	s_waitcnt lgkmcnt(0)
	s_setprio 1
	s_waitcnt lgkmcnt(0)
	v_mfma_f32_16x16x32_bf16 v[126:129], v[140:143], v[156:159], v[126:129]
	v_mfma_f32_16x16x32_bf16 v[122:125], v[148:151], v[156:159], v[122:125]
	v_mfma_f32_16x16x32_bf16 v[110:113], v[140:143], v[188:191], v[110:113]
	v_mfma_f32_16x16x32_bf16 v[106:109], v[148:151], v[188:191], v[106:109]
	v_mfma_f32_16x16x32_bf16 v[126:129], v[144:147], v[176:179], v[126:129]
	v_mfma_f32_16x16x32_bf16 v[122:125], v[152:155], v[176:179], v[122:125]
	v_mfma_f32_16x16x32_bf16 v[118:121], v[140:143], v[180:183], v[118:121]
	v_mfma_f32_16x16x32_bf16 v[114:117], v[148:151], v[180:183], v[114:117]
	v_mfma_f32_16x16x32_bf16 v[110:113], v[144:147], v[192:195], v[110:113]
	v_mfma_f32_16x16x32_bf16 v[106:109], v[152:155], v[192:195], v[106:109]
	v_mfma_f32_16x16x32_bf16 v[102:105], v[140:143], v[200:203], v[102:105]
	v_mfma_f32_16x16x32_bf16 v[98:101], v[148:151], v[200:203], v[98:101]
	v_mfma_f32_16x16x32_bf16 v[160:163], v[144:147], v[184:187], v[118:121]
	v_mfma_f32_16x16x32_bf16 v[208:211], v[152:155], v[184:187], v[114:117]
	v_mfma_f32_16x16x32_bf16 v[212:215], v[144:147], v[204:207], v[102:105]
	v_mfma_f32_16x16x32_bf16 v[216:219], v[152:155], v[204:207], v[98:101]
	s_setprio 0
	s_barrier
	s_nop 1
	ds_read_b128 v[98:101], v173
	ds_read_b128 v[102:105], v173 offset:1024
	ds_read_b128 v[114:117], v173 offset:2048
	ds_read_b128 v[118:121], v173 offset:3072
	s_barrier
	s_waitcnt lgkmcnt(0)
	s_setprio 1
	s_waitcnt lgkmcnt(0)
	v_mfma_f32_16x16x32_bf16 v[94:97], v[98:101], v[156:159], v[94:97]
	v_mfma_f32_16x16x32_bf16 v[90:93], v[114:117], v[156:159], v[90:93]
	v_mfma_f32_16x16x32_bf16 v[78:81], v[98:101], v[188:191], v[78:81]
	v_mfma_f32_16x16x32_bf16 v[74:77], v[114:117], v[188:191], v[74:77]
	v_mfma_f32_16x16x32_bf16 v[94:97], v[102:105], v[176:179], v[94:97]
	v_mfma_f32_16x16x32_bf16 v[90:93], v[118:121], v[176:179], v[90:93]
	v_mfma_f32_16x16x32_bf16 v[86:89], v[98:101], v[180:183], v[86:89]
	v_mfma_f32_16x16x32_bf16 v[82:85], v[114:117], v[180:183], v[82:85]
	v_mfma_f32_16x16x32_bf16 v[78:81], v[102:105], v[192:195], v[78:81]
	v_mfma_f32_16x16x32_bf16 v[74:77], v[118:121], v[192:195], v[74:77]
	v_mfma_f32_16x16x32_bf16 v[70:73], v[98:101], v[200:203], v[70:73]
	v_mfma_f32_16x16x32_bf16 v[66:69], v[114:117], v[200:203], v[66:69]
	v_mfma_f32_16x16x32_bf16 v[156:159], v[102:105], v[184:187], v[86:89]
	v_mfma_f32_16x16x32_bf16 v[176:179], v[118:121], v[184:187], v[82:85]
	v_mfma_f32_16x16x32_bf16 v[180:183], v[102:105], v[204:207], v[70:73]
	v_mfma_f32_16x16x32_bf16 v[184:187], v[118:121], v[204:207], v[66:69]
	s_setprio 0
	s_barrier
	s_nop 1
	ds_read_b128 v[66:69], v169 offset:16384
	ds_read_b128 v[70:73], v169 offset:17408
	ds_read_b128 v[82:85], v170 offset:16384
	ds_read_b128 v[86:89], v170 offset:17408
	ds_read_b128 v[188:191], v171 offset:16384
	ds_read_b128 v[192:195], v171 offset:17408
	ds_read_b128 v[200:203], v172 offset:16384
	ds_read_b128 v[204:207], v172 offset:17408
	s_waitcnt vmcnt(4)
	s_barrier
	s_waitcnt lgkmcnt(0)
	s_setprio 1
	s_waitcnt lgkmcnt(0)
	v_mfma_f32_16x16x32_bf16 v[62:65], v[140:143], v[66:69], v[62:65]
	v_mfma_f32_16x16x32_bf16 v[58:61], v[148:151], v[66:69], v[58:61]
	v_mfma_f32_16x16x32_bf16 v[46:49], v[140:143], v[188:191], v[46:49]
	v_mfma_f32_16x16x32_bf16 v[42:45], v[148:151], v[188:191], v[42:45]
	v_mfma_f32_16x16x32_bf16 v[62:65], v[144:147], v[70:73], v[62:65]
	v_mfma_f32_16x16x32_bf16 v[58:61], v[152:155], v[70:73], v[58:61]
	v_mfma_f32_16x16x32_bf16 v[54:57], v[140:143], v[82:85], v[54:57]
	v_mfma_f32_16x16x32_bf16 v[50:53], v[148:151], v[82:85], v[50:53]
	v_mfma_f32_16x16x32_bf16 v[46:49], v[144:147], v[192:195], v[46:49]
	v_mfma_f32_16x16x32_bf16 v[42:45], v[152:155], v[192:195], v[42:45]
	v_mfma_f32_16x16x32_bf16 v[38:41], v[140:143], v[200:203], v[38:41]
	v_mfma_f32_16x16x32_bf16 v[34:37], v[148:151], v[200:203], v[34:37]
	v_mfma_f32_16x16x32_bf16 v[220:223], v[144:147], v[86:89], v[54:57]
	v_mfma_f32_16x16x32_bf16 v[224:227], v[152:155], v[86:89], v[50:53]
	v_mfma_f32_16x16x32_bf16 v[140:143], v[144:147], v[204:207], v[38:41]
	v_mfma_f32_16x16x32_bf16 v[144:147], v[152:155], v[204:207], v[34:37]
	s_setprio 0
	s_setprio 1
	v_mfma_f32_16x16x32_bf16 v[30:33], v[98:101], v[66:69], v[30:33]
	v_mfma_f32_16x16x32_bf16 v[26:29], v[114:117], v[66:69], v[26:29]
	v_mfma_f32_16x16x32_bf16 v[14:17], v[98:101], v[188:191], v[14:17]
	v_mfma_f32_16x16x32_bf16 v[10:13], v[114:117], v[188:191], v[10:13]
	v_mfma_f32_16x16x32_bf16 v[30:33], v[102:105], v[70:73], v[30:33]
	v_mfma_f32_16x16x32_bf16 v[26:29], v[118:121], v[70:73], v[26:29]
	v_mfma_f32_16x16x32_bf16 v[22:25], v[98:101], v[82:85], v[22:25]
	v_mfma_f32_16x16x32_bf16 v[18:21], v[114:117], v[82:85], v[18:21]
	v_mfma_f32_16x16x32_bf16 v[14:17], v[102:105], v[192:195], v[14:17]
	v_mfma_f32_16x16x32_bf16 v[10:13], v[118:121], v[192:195], v[10:13]
	v_mfma_f32_16x16x32_bf16 v[6:9], v[98:101], v[200:203], v[6:9]
	v_mfma_f32_16x16x32_bf16 v[2:5], v[114:117], v[200:203], v[2:5]
	v_mfma_f32_16x16x32_bf16 v[148:151], v[102:105], v[86:89], v[22:25]
	v_mfma_f32_16x16x32_bf16 v[152:155], v[118:121], v[86:89], v[18:21]
	v_mfma_f32_16x16x32_bf16 v[188:191], v[102:105], v[204:207], v[6:9]
	v_mfma_f32_16x16x32_bf16 v[192:195], v[118:121], v[204:207], v[2:5]
	s_setprio 0
	s_barrier
	s_nop 1
	ds_read_b128 v[2:5], v174
	ds_read_b128 v[6:9], v174 offset:1024
	ds_read_b128 v[200:203], v174 offset:2048
	ds_read_b128 v[204:207], v174 offset:3072
	ds_read_b128 v[18:21], v169 offset:32768
	ds_read_b128 v[22:25], v169 offset:33792
	ds_read_b128 v[34:37], v170 offset:32768
	ds_read_b128 v[38:41], v170 offset:33792
	ds_read_b128 v[50:53], v171 offset:32768
	ds_read_b128 v[54:57], v171 offset:33792
	ds_read_b128 v[228:231], v172 offset:32768
	ds_read_b128 v[232:235], v172 offset:33792
	s_waitcnt vmcnt(2)
	s_barrier
	s_waitcnt lgkmcnt(0)
	s_setprio 1
	s_waitcnt lgkmcnt(0)
	v_mfma_f32_16x16x32_bf16 v[66:69], v[2:5], v[18:21], v[126:129]
	v_mfma_f32_16x16x32_bf16 v[114:117], v[6:9], v[22:25], v[66:69]
	v_mfma_f32_16x16x32_bf16 v[66:69], v[200:203], v[18:21], v[122:125]
	v_mfma_f32_16x16x32_bf16 v[118:121], v[204:207], v[22:25], v[66:69]
	v_mfma_f32_16x16x32_bf16 v[66:69], v[2:5], v[34:37], v[160:163]
	v_mfma_f32_16x16x32_bf16 v[98:101], v[6:9], v[38:41], v[66:69]
	v_mfma_f32_16x16x32_bf16 v[66:69], v[200:203], v[34:37], v[208:211]
	v_mfma_f32_16x16x32_bf16 v[102:105], v[204:207], v[38:41], v[66:69]
	v_mfma_f32_16x16x32_bf16 v[66:69], v[2:5], v[50:53], v[110:113]
	v_mfma_f32_16x16x32_bf16 v[82:85], v[6:9], v[54:57], v[66:69]
	v_mfma_f32_16x16x32_bf16 v[66:69], v[200:203], v[50:53], v[106:109]
	v_mfma_f32_16x16x32_bf16 v[86:89], v[204:207], v[54:57], v[66:69]
	v_mfma_f32_16x16x32_bf16 v[66:69], v[2:5], v[228:231], v[212:215]
	v_mfma_f32_16x16x32_bf16 v[70:73], v[200:203], v[228:231], v[216:219]
	v_mfma_f32_16x16x32_bf16 v[66:69], v[6:9], v[232:235], v[66:69]
	v_mfma_f32_16x16x32_bf16 v[70:73], v[204:207], v[232:235], v[70:73]
	s_setprio 0
	s_barrier
	ds_read_b128 v[160:163], v175
	ds_read_b128 v[208:211], v175 offset:1024
	ds_read_b128 v[212:215], v175 offset:2048
	ds_read_b128 v[216:219], v175 offset:3072
	s_waitcnt vmcnt(0)
	s_barrier
	s_waitcnt lgkmcnt(0)
	s_setprio 1
	s_waitcnt lgkmcnt(0)
	v_mfma_f32_16x16x32_bf16 v[94:97], v[160:163], v[18:21], v[94:97]
	v_mfma_f32_16x16x32_bf16 v[18:21], v[212:215], v[18:21], v[90:93]
	v_mfma_f32_16x16x32_bf16 v[122:125], v[216:219], v[22:25], v[18:21]
	v_mfma_f32_16x16x32_bf16 v[18:21], v[160:163], v[34:37], v[156:159]
	v_mfma_f32_16x16x32_bf16 v[110:113], v[208:211], v[38:41], v[18:21]
	v_mfma_f32_16x16x32_bf16 v[18:21], v[212:215], v[34:37], v[176:179]
	v_mfma_f32_16x16x32_bf16 v[106:109], v[216:219], v[38:41], v[18:21]
	v_mfma_f32_16x16x32_bf16 v[18:21], v[160:163], v[50:53], v[78:81]
	v_mfma_f32_16x16x32_bf16 v[126:129], v[208:211], v[22:25], v[94:97]
	v_mfma_f32_16x16x32_bf16 v[94:97], v[208:211], v[54:57], v[18:21]
	v_mfma_f32_16x16x32_bf16 v[18:21], v[212:215], v[50:53], v[74:77]
	v_mfma_f32_16x16x32_bf16 v[90:93], v[216:219], v[54:57], v[18:21]
	v_mfma_f32_16x16x32_bf16 v[18:21], v[160:163], v[228:231], v[180:183]
	v_mfma_f32_16x16x32_bf16 v[78:81], v[208:211], v[232:235], v[18:21]
	v_mfma_f32_16x16x32_bf16 v[18:21], v[212:215], v[228:231], v[184:187]
	v_mfma_f32_16x16x32_bf16 v[74:77], v[216:219], v[232:235], v[18:21]
	s_setprio 0
	s_barrier
	ds_read_b128 v[156:159], v169 offset:49152
	ds_read_b128 v[176:179], v169 offset:50176
	ds_read_b128 v[180:183], v170 offset:49152
	ds_read_b128 v[184:187], v170 offset:50176
	ds_read_b128 v[228:231], v171 offset:49152
	ds_read_b128 v[232:235], v171 offset:50176
	ds_read_b128 v[236:239], v172 offset:49152
	ds_read_b128 v[240:243], v172 offset:50176
	s_barrier
	s_waitcnt lgkmcnt(0)
	s_setprio 1
	s_waitcnt lgkmcnt(0)
	v_mfma_f32_16x16x32_bf16 v[18:21], v[2:5], v[156:159], v[62:65]
	v_mfma_f32_16x16x32_bf16 v[50:53], v[6:9], v[176:179], v[18:21]
	v_mfma_f32_16x16x32_bf16 v[18:21], v[200:203], v[156:159], v[58:61]
	v_mfma_f32_16x16x32_bf16 v[54:57], v[204:207], v[176:179], v[18:21]
	v_mfma_f32_16x16x32_bf16 v[18:21], v[2:5], v[180:183], v[220:223]
	v_mfma_f32_16x16x32_bf16 v[34:37], v[6:9], v[184:187], v[18:21]
	v_mfma_f32_16x16x32_bf16 v[18:21], v[200:203], v[180:183], v[224:227]
	v_mfma_f32_16x16x32_bf16 v[38:41], v[204:207], v[184:187], v[18:21]
	v_mfma_f32_16x16x32_bf16 v[18:21], v[2:5], v[228:231], v[46:49]
	v_mfma_f32_16x16x32_bf16 v[2:5], v[2:5], v[236:239], v[140:143]
	v_mfma_f32_16x16x32_bf16 v[18:21], v[6:9], v[232:235], v[18:21]
	v_mfma_f32_16x16x32_bf16 v[22:25], v[200:203], v[228:231], v[42:45]
	v_mfma_f32_16x16x32_bf16 v[2:5], v[6:9], v[240:243], v[2:5]
	v_mfma_f32_16x16x32_bf16 v[6:9], v[200:203], v[236:239], v[144:147]
	v_mfma_f32_16x16x32_bf16 v[22:25], v[204:207], v[232:235], v[22:25]
	v_mfma_f32_16x16x32_bf16 v[6:9], v[204:207], v[240:243], v[6:9]
	s_setprio 0
	s_setprio 1
	v_mfma_f32_16x16x32_bf16 v[26:29], v[212:215], v[156:159], v[26:29]
	v_mfma_f32_16x16x32_bf16 v[58:61], v[216:219], v[176:179], v[26:29]
	v_mfma_f32_16x16x32_bf16 v[26:29], v[160:163], v[180:183], v[148:151]
	v_mfma_f32_16x16x32_bf16 v[46:49], v[208:211], v[184:187], v[26:29]
	v_mfma_f32_16x16x32_bf16 v[26:29], v[212:215], v[180:183], v[152:155]
	v_mfma_f32_16x16x32_bf16 v[10:13], v[212:215], v[228:231], v[10:13]
	v_mfma_f32_16x16x32_bf16 v[30:33], v[160:163], v[156:159], v[30:33]
	v_mfma_f32_16x16x32_bf16 v[42:45], v[216:219], v[184:187], v[26:29]
	v_mfma_f32_16x16x32_bf16 v[14:17], v[160:163], v[228:231], v[14:17]
	v_mfma_f32_16x16x32_bf16 v[26:29], v[216:219], v[232:235], v[10:13]
	v_mfma_f32_16x16x32_bf16 v[10:13], v[160:163], v[236:239], v[188:191]
	v_mfma_f32_16x16x32_bf16 v[62:65], v[208:211], v[176:179], v[30:33]
	v_mfma_f32_16x16x32_bf16 v[30:33], v[208:211], v[232:235], v[14:17]
	v_mfma_f32_16x16x32_bf16 v[14:17], v[208:211], v[240:243], v[10:13]
	v_mfma_f32_16x16x32_bf16 v[10:13], v[212:215], v[236:239], v[192:195]
	v_mfma_f32_16x16x32_bf16 v[10:13], v[216:219], v[240:243], v[10:13]
	s_setprio 0
	s_barrier
	s_and_saveexec_b64 s[6:7], s[2:3]
	s_cbranch_execz .LBB0_2583
	s_barrier
